# speedup vs baseline: 1.0096x; 1.0096x over previous
; #define LAS __attribute__((address_space(3)))
; __device__ __forceinline__ int opaque_tid() { int t; asm volatile("v_mov_b32 %0, %1" : "=v"(t) : "v"(threadIdx.x)); return t; }
; __device__ __forceinline__ int v_rd_base(int lane) { return ((lane & 3) << 3) | (((lane >> 2) & 3) << 6) | (((lane >> 4) & 1) << 5) | (((lane >> 5) & 1) << 8); }
; __device__ __forceinline__ void attn_body256(const bf16_t* __restrict__ Qb, const bf16_t* __restrict__ Kh, const bf16_t* __restrict__ Vh,
;                                              bf16_t* Ob, int seq, unsigned char* lds, float lam, int MODE, bf16_t* Ab, const float* wsub) {
;   const int tid = opaque_tid(), wid = __builtin_amdgcn_readfirstlane(tid >> 6), lane = tid & 63, r32 = lane & 31, hi = lane >> 5;
;   LAS unsigned char* ldsl = (LAS unsigned char*)lds;
;   float* ws = (float*)(lds + A2_WS) + wid * 64; float* li_l = ws; float* al_l = ws + 32;
;   unsigned koff[2], voff[4];
; #pragma unroll
;   for (int i = 0; i < 2; ++i) { const int o = i * 8192 + tid * 16; const int row = o >> 8; const int colB = (o & 255) ^ ((row & 7) << 4);
;     koff[i] = (unsigned)(row * LDK + (colB >> 1));
;     const int sub = o >> 9, kk = (sub >> 2) * 8 + ((o & 511) >> 6), c = (sub & 3) * 32 + (((o & 511) >> 1) & 31);
;     const int k = (kk & ~0xC) | ((kk & 4) << 1) | ((kk & 8) >> 1);
;     voff[i] = (unsigned)(k * LDK + c); voff[2 + i] = (unsigned)(k * LDK + 128 + c); }
;     ...
;   const int NT = seq / KVBLK;
;   A2_DMA(0, 0); A2_DMA(1, 1);
;   float m_reg = -1e30f, l_reg = 0; f32x16 o[8] = {}; bf16x8 qr[8];
;   const bf16_t* Qw = Qb + (long)(wid * QBLK + r32) * LDQ + hi * 8;
; #pragma unroll
;   for (int d0 = 0; d0 < 8; ++d0) qr[d0] = *reinterpret_cast<const bf16x8*>(Qw + d0 * 16);
;   const int vb0 = (int)(uintptr_t)lds + v_rd_base(lane);
;   asm volatile("s_waitcnt vmcnt(0)" ::: "memory"); __syncthreads();
.LBB0_669:
	s_and_b32 s2, s18, 1
	s_lshl_b64 s[10:11], s[62:63], 11
	s_lshl_b64 s[6:7], s[62:63], 12
	s_add_u32 s9, s96, s6
	s_addc_u32 s12, s97, s7
	s_lshl_b32 s16, s8, 8
	s_lshl_b32 s6, s2, 7
	s_or_b32 s6, s16, s6
	s_ashr_i32 s7, s6, 31
	s_lshl_b64 s[14:15], s[6:7], 1
	s_add_u32 s6, s9, s14
	s_addc_u32 s7, s12, s15
	s_lshl_b64 s[8:9], s[0:1], 1
	s_add_u32 s0, s60, s8
	s_addc_u32 s1, s53, s9
	s_add_u32 s12, s0, s14
	s_addc_u32 s13, s1, s15
	v_mov_b32 v16, v231
	v_lshrrev_b32_e32 v245, 7, v231
	v_lshlrev_b32_e32 v245, 3, v245
	v_bfe_u32 v244, v231, 1, 3
	v_add_u32_e32 v245, v245, v244
	v_lshlrev_b32_e32 v245, 11, v245
	v_bfe_u32 v244, v231, 4, 3
	v_lshl_add_u32 v245, v244, 4, v245
	v_and_b32_e32 v244, 1, v231
	v_lshl_add_u32 v245, v244, 3, v245
	s_add_u32 s20, s61, s8
	v_lshlrev_b32_e32 v17, 4, v16
	v_add_u32_e32 v6, 0x2000, v17
	s_addc_u32 s21, s68, s9
	s_ashr_i32 s17, s16, 31
	v_ashrrev_i32_e32 v8, 8, v6
	s_lshl_b64 s[0:1], s[16:17], 1
	v_and_b32_e32 v3, 0xf0, v17
	v_lshlrev_b32_e32 v6, 4, v8
	s_movk_i32 s26, 0x70
	s_add_u32 s16, s20, s0
	v_lshrrev_b32_e32 v0, 1, v16
	v_ashrrev_i32_e32 v2, 4, v16
	v_bitop3_b32 v3, v6, v3, s26 bitop3:0x6c
	s_addc_u32 s17, s21, s1
	v_readfirstlane_b32 s20, v16
	v_and_b32_e32 v22, 8, v0
	v_and_b32_e32 v0, 0x70, v16
	s_movk_i32 s21, 0xf0
	v_lshrrev_b32_e32 v4, 1, v2
	v_lshrrev_b32_e32 v3, 1, v3
	s_ashr_i32 s23, s20, 6
	v_bfe_u32 v18, v16, 2, 2
	v_lshlrev_b32_e32 v20, 3, v16
	v_bitop3_b32 v0, v17, v0, s21 bitop3:0x6c
	v_and_b32_e32 v4, 4, v4
	v_lshl_or_b32 v6, v8, 11, v3
	v_and_b32_e32 v3, 0x1ffff0, v8
	v_lshrrev_b32_e32 v8, 1, v8
	v_and_b32_e32 v19, 0x60, v16
	v_and_b32_e32 v21, 24, v20
	v_or_b32_e32 v7, v22, v18
	v_lshrrev_b32_e32 v0, 1, v0
	v_and_or_b32 v23, v2, -16, v4
	v_and_b32_e32 v8, 4, v8
	s_lshl_b32 s21, s23, 10
	v_or_b32_e32 v5, v21, v19
	v_lshl_or_b32 v0, v2, 11, v0
	v_or_b32_e32 v2, v7, v23
	v_or3_b32 v3, v3, v8, v7
	s_add_i32 s21, s21, 0
	v_lshl_or_b32 v2, v2, 11, v5
	v_mov_b32_e32 v2, v245
	v_lshlrev_b32_e32 v24, 11, v3
	s_add_i32 s22, s21, 0x10000
	v_lshlrev_b64 v[12:13], 1, v[0:1]
	v_mov_b32_e32 v3, v1
	v_or_b32_e32 v4, 0x80, v2
	v_lshl_add_u64 v[14:15], s[12:13], 0, v[12:13]
	s_mov_b32 m0, s22
	v_lshlrev_b64 v[2:3], 1, v[2:3]
	s_add_i32 s24, s21, 0x4000
	global_load_lds_dwordx4 v[14:15], off
	v_lshl_add_u64 v[14:15], s[16:17], 0, v[2:3]
	s_mov_b32 m0, s21
	s_mov_b64 s[30:31], 0x100
	v_mov_b32_e32 v7, v1
	s_and_b32 s20, s20, 0x3fffffc0
	v_or_b32_e32 v8, v24, v5
	v_add_u32_e32 v8, 0x10000, v245
	global_load_lds_dwordx4 v[14:15], off
	v_lshl_add_u64 v[14:15], v[14:15], 0, s[30:31]
	s_mov_b32 m0, s24
	v_lshlrev_b64 v[6:7], 1, v[6:7]
	v_mov_b32_e32 v9, v1
	s_lshl_b32 s20, s20, 2
	v_or_b32_e32 v10, 0x80, v8
	global_load_lds_dwordx4 v[14:15], off
	v_lshl_add_u64 v[14:15], s[12:13], 0, v[6:7]
	s_add_i32 m0, s21, 0x12000
	v_lshlrev_b64 v[8:9], 1, v[8:9]
	s_add_i32 s20, s20, 0
	global_load_lds_dwordx4 v[14:15], off
	v_lshl_add_u64 v[14:15], s[16:17], 0, v[8:9]
	s_add_i32 m0, s21, 0x2000
	s_add_i32 s20, s20, 0x18000
	global_load_lds_dwordx4 v[14:15], off
	s_add_i32 m0, s21, 0x6000
	s_add_u32 s12, s12, 0x40000
	s_addc_u32 s13, s13, 0
	v_lshl_add_u64 v[14:15], v[14:15], 0, s[30:31]
	s_add_u32 s16, s16, 0x40000
	global_load_lds_dwordx4 v[14:15], off
	s_addc_u32 s17, s17, 0
	s_add_i32 m0, s21, 0x14000
	s_add_i32 s24, s21, 0x8000
	v_lshl_add_u64 v[14:15], s[12:13], 0, v[12:13]
	v_mov_b32_e32 v5, v1
	s_add_i32 s25, s21, 0xc000
	global_load_lds_dwordx4 v[14:15], off
	v_lshl_add_u64 v[2:3], s[16:17], 0, v[2:3]
	s_mov_b32 m0, s24
	v_mov_b32_e32 v11, v1
	global_load_lds_dwordx4 v[2:3], off
	v_lshl_add_u64 v[2:3], v[4:5], 1, s[16:17]
	s_mov_b32 m0, s25
	v_and_b32_e32 v228, 31, v16
	global_load_lds_dwordx4 v[2:3], off
	v_lshl_add_u64 v[2:3], s[12:13], 0, v[6:7]
	s_add_i32 m0, s21, 0x16000
	s_lshl_b32 s12, s23, 5
	global_load_lds_dwordx4 v[2:3], off
	v_lshl_add_u64 v[2:3], s[16:17], 0, v[8:9]
	s_add_i32 m0, s21, 0xa000
	v_bfe_u32 v229, v16, 5, 1
	global_load_lds_dwordx4 v[2:3], off
	v_lshl_add_u64 v[2:3], v[10:11], 1, s[16:17]
	s_add_i32 m0, s21, 0xe000
	v_lshlrev_b32_e32 v0, 4, v229
	global_load_lds_dwordx4 v[2:3], off
	v_and_b32_e32 v2, 15, v231
	v_or_b32_e32 v2, s12, v2
	v_mov_b32_e32 v3, 0
	v_lshlrev_b64 v[2:3], 12, v[2:3]
	v_lshl_add_u64 v[2:3], s[6:7], 0, v[2:3]
	v_bfe_u32 v194, v231, 4, 2
	v_lshlrev_b32_e32 v194, 4, v194
	v_mov_b32_e32 v195, 0
	v_lshl_add_u64 v[2:3], v[2:3], 0, v[194:195]
	global_load_dwordx4 v[162:165], v[2:3], off
	global_load_dwordx4 v[166:169], v[2:3], off offset:64
	global_load_dwordx4 v[170:173], v[2:3], off offset:128
	global_load_dwordx4 v[174:177], v[2:3], off offset:192
	v_mov_b32_e32 v194, 0x10000
	v_lshl_add_u64 v[2:3], v[2:3], 0, v[194:195]
	global_load_dwordx4 v[178:181], v[2:3], off
	global_load_dwordx4 v[182:185], v[2:3], off offset:64
	global_load_dwordx4 v[186:189], v[2:3], off offset:128
	global_load_dwordx4 v[190:193], v[2:3], off offset:192
	v_and_b32_e32 v8, 0x70, v17
	s_movk_i32 s6, 0x60
	v_bitop3_b32 v236, v0, v8, s6 bitop3:0x36
	s_movk_i32 s6, 0x80
	v_bitop3_b32 v237, v0, v8, s6 bitop3:0x36
	s_movk_i32 s6, 0xa0
	v_bitop3_b32 v240, v0, v8, s6 bitop3:0x36
	s_movk_i32 s6, 0xc0
	s_cmp_lg_u32 0, -1
	v_and_b32_e32 v2, 63, v16
	v_lshlrev_b32_e32 v3, 1, v16
	v_and_b32_e32 v4, 0x118, v20
	v_bitop3_b32 v241, v0, v8, s6 bitop3:0x36
	s_movk_i32 s6, 0xe0
	s_cselect_b32 s16, 0, 0
	s_lshl_b32 s23, s19, 18
	v_and_b32_e32 v5, 0xc0, v17
	v_bitop3_b32 v247, v0, v8, s6 bitop3:0x36
	v_cmp_gt_u32_e64 s[6:7], 32, v2
	v_and_or_b32 v2, v3, 32, v4
	s_add_u32 s14, s8, s14
	v_add3_u32 v248, v5, s16, v2
	s_addc_u32 s15, s9, s15
	v_readlane_b32 s16, v254, 41
	s_add_u32 s14, s16, s14
	v_readlane_b32 s16, v254, 42
	s_addc_u32 s15, s16, s15
	s_add_u32 s8, s8, s0
	s_addc_u32 s9, s9, s1
	v_or3_b32 v2, v23, v22, v18
	v_lshlrev_b32_e32 v2, 11, v2
	s_add_u32 s8, s88, s8
	v_or3_b32 v2, v2, v19, v21
	v_mov_b32_e32 v2, v245
	v_mov_b32_e32 v3, v1
	s_addc_u32 s9, s89, s9
	s_waitcnt vmcnt(0)
; #define SBAR() __builtin_amdgcn_sched_barrier(0)
; __device__ __forceinline__ int v_rd_base(int lane) { return ((lane & 3) << 3) | (((lane >> 2) & 3) << 6) | (((lane >> 4) & 1) << 5) | (((lane >> 5) & 1) << 8); }
; __device__ __forceinline__ void qkt(f32x16& p0, f32x16& p1, const bf16_t* Ks, const bf16x8* qr, int r32, int hi) {
;   p0 = f32x16{}; p1 = f32x16{};
;   for (int d0 = 0; d0 < 8; ++d0) { int cb = (d0 * 16 + hi * 8) * 2;
;     bf16x8 b0 = *reinterpret_cast<const bf16x8*>((const char*)Ks + KSWZ(r32, cb));
;     bf16x8 b1 = *reinterpret_cast<const bf16x8*>((const char*)Ks + KSWZ(32 + r32, cb));
;     p0 = __builtin_amdgcn_mfma_f32_32x32x16_bf16(b0, qr[d0], p0, 0, 0, 0);
;     p1 = __builtin_amdgcn_mfma_f32_32x32x16_bf16(b1, qr[d0], p1, 0, 0, 0); }
; __device__ __forceinline__ void attn_body256(const bf16_t* __restrict__ Qb, const bf16_t* __restrict__ Kh, const bf16_t* __restrict__ Vh,
;                                              bf16_t* Ob, int seq, unsigned char* lds, float lam, int MODE, bf16_t* Ab, const float* wsub) {
;     ...
;   float m_reg = -1e30f, l_reg = 0; f32x16 o[8] = {}; bf16x8 qr[8];
;   const bf16_t* Qw = Qb + (long)(wid * QBLK + r32) * LDQ + hi * 8;
; #pragma unroll
;   for (int d0 = 0; d0 < 8; ++d0) qr[d0] = *reinterpret_cast<const bf16x8*>(Qw + d0 * 16);
;   const int vb0 = (int)(uintptr_t)lds + v_rd_base(lane);
;   asm volatile("s_waitcnt vmcnt(0)" ::: "memory"); __syncthreads();
;   for (int j = 0; j < NT; ++j) {
;     const int b = j & 1;
;     f32x16 p0, p1; float mn, alpha; bf16x8 pa0, pa1, pa2, pa3;
;     SBAR(); qkt(p0, p1, (const bf16_t*)(lds + A2_KOFF + b * A2_KBUF), qr, r32, hi);
	v_bitop3_b32 v232, v0, v17, s26 bitop3:0x78
	v_lshl_add_u64 v[224:225], v[2:3], 1, s[8:9]
	v_or3_b32 v2, v24, v19, v21
	v_add_u32_e32 v2, 0x10000, v245
	v_mov_b32_e32 v16, v1
	v_mov_b32_e32 v17, v1
	v_bitop3_b32 v233, v0, v8, 32 bitop3:0x36
	v_bitop3_b32 v234, v0, v8, 64 bitop3:0x36
	v_lshl_add_u64 v[220:221], s[14:15], 0, v[12:13]
	v_lshl_add_u64 v[222:223], s[14:15], 0, v[6:7]
	v_lshl_add_u64 v[226:227], v[2:3], 1, s[8:9]
	v_mov_b32_e32 v2, v1
	v_mov_b32_e32 v4, v1
	v_mov_b32_e32 v5, v1
	v_mov_b32_e32 v6, v1
	v_mov_b32_e32 v7, v1
	v_mov_b32_e32 v8, v1
	v_mov_b32_e32 v9, v1
	v_mov_b32_e32 v10, v1
	v_mov_b32_e32 v12, v1
	v_mov_b32_e32 v13, v1
	v_mov_b32_e32 v14, v1
	v_mov_b32_e32 v15, v1
	v_mov_b64_e32 v[128:129], v[16:17]
	v_mov_b64_e32 v[112:113], v[16:17]
	v_mov_b64_e32 v[96:97], v[16:17]
	v_mov_b64_e32 v[80:81], v[16:17]
	v_mov_b64_e32 v[64:65], v[16:17]
	v_mov_b64_e32 v[48:49], v[16:17]
	v_mov_b64_e32 v[32:33], v[16:17]
	s_mov_b32 s13, 2
	v_lshlrev_b32_e32 v230, 8, v228
	v_lshl_add_u32 v238, v228, 2, s20
	v_mov_b32_e32 v250, 0
	v_mov_b32_e32 v249, 0xf149f2ca
	s_mov_b64 s[14:15], 0
	v_mov_b64_e32 v[126:127], v[14:15]
	v_mov_b64_e32 v[124:125], v[12:13]
	v_mov_b64_e32 v[122:123], v[10:11]
	v_mov_b64_e32 v[120:121], v[8:9]
	v_mov_b64_e32 v[118:119], v[6:7]
	v_mov_b64_e32 v[116:117], v[4:5]
	v_mov_b64_e32 v[114:115], v[2:3]
	v_mov_b64_e32 v[110:111], v[14:15]
	v_mov_b64_e32 v[108:109], v[12:13]
	v_mov_b64_e32 v[106:107], v[10:11]
	v_mov_b64_e32 v[104:105], v[8:9]
	v_mov_b64_e32 v[102:103], v[6:7]
	v_mov_b64_e32 v[100:101], v[4:5]
	v_mov_b64_e32 v[98:99], v[2:3]
	v_mov_b64_e32 v[94:95], v[14:15]
	v_mov_b64_e32 v[92:93], v[12:13]
	v_mov_b64_e32 v[90:91], v[10:11]
	v_mov_b64_e32 v[88:89], v[8:9]
	v_mov_b64_e32 v[86:87], v[6:7]
	v_mov_b64_e32 v[84:85], v[4:5]
	v_mov_b64_e32 v[82:83], v[2:3]
	v_mov_b64_e32 v[78:79], v[14:15]
	v_mov_b64_e32 v[76:77], v[12:13]
	v_mov_b64_e32 v[74:75], v[10:11]
	v_mov_b64_e32 v[72:73], v[8:9]
	v_mov_b64_e32 v[70:71], v[6:7]
	v_mov_b64_e32 v[68:69], v[4:5]
	v_mov_b64_e32 v[66:67], v[2:3]
	v_mov_b64_e32 v[62:63], v[14:15]
	v_mov_b64_e32 v[60:61], v[12:13]
	v_mov_b64_e32 v[58:59], v[10:11]
	v_mov_b64_e32 v[56:57], v[8:9]
	v_mov_b64_e32 v[54:55], v[6:7]
	v_mov_b64_e32 v[52:53], v[4:5]
	v_mov_b64_e32 v[50:51], v[2:3]
	v_mov_b64_e32 v[46:47], v[14:15]
	v_mov_b64_e32 v[44:45], v[12:13]
	v_mov_b64_e32 v[42:43], v[10:11]
	v_mov_b64_e32 v[40:41], v[8:9]
	v_mov_b64_e32 v[38:39], v[6:7]
	v_mov_b64_e32 v[36:37], v[4:5]
	v_mov_b64_e32 v[34:35], v[2:3]
	v_mov_b64_e32 v[30:31], v[14:15]
	v_mov_b64_e32 v[28:29], v[12:13]
	v_mov_b64_e32 v[26:27], v[10:11]
	v_mov_b64_e32 v[24:25], v[8:9]
	v_mov_b64_e32 v[22:23], v[6:7]
	v_mov_b64_e32 v[20:21], v[4:5]
	v_mov_b64_e32 v[18:19], v[2:3]
	v_and_b32_e32 v237, 15, v231
	v_bfe_u32 v240, v231, 4, 2
	v_and_b32_e32 v241, 7, v237
	v_lshlrev_b32_e32 v241, 4, v241
	v_lshlrev_b32_e32 v247, 4, v240
	v_xor_b32_e32 v232, v247, v241
	v_add_u32_e32 v247, 64, v247
	v_xor_b32_e32 v233, v247, v241
	v_lshlrev_b32_e32 v247, 8, v237
	v_add_u32_e32 v232, v232, v247
	v_add_u32_e32 v233, v233, v247
	v_and_b32_e32 v247, 1, v240
	v_lshlrev_b32_e32 v248, 7, v247
	v_lshrrev_b32_e32 v247, 1, v240
	v_lshl_add_u32 v248, v247, 11, v248
	v_bfe_u32 v247, v231, 2, 2
	v_lshl_add_u32 v248, v247, 5, v248
	v_and_b32_e32 v247, 3, v231
	v_lshl_add_u32 v248, v247, 3, v248
	v_mov_b32_e32 v249, 0xf149f2ca
	v_mov_b32_e32 v246, 0xf149f2ca
	v_mov_b32_e32 v250, 0
	v_mov_b32_e32 v234, 0
	s_movk_i32 s62, 0x7fff
	s_waitcnt vmcnt(0) lgkmcnt(0)
	s_barrier
	s_mov_b32 s98, 0
	s_mov_b32 s99, 0x8000
	s_mov_b32 s100, 0x19000
	s_cmpk_ge_u32 s21, 0x1000
	s_cbranch_scc1 .Lat_y_qk
.Lat_x_top:
	s_add_i32 s8, s13, -2
	s_and_b32 s25, s8, 1
	s_lshl_b32 s24, s25, 14
	s_add_i32 s8, s24, 0x10000
	v_add_u32_e32 v230, s8, v232
	v_add_u32_e32 v247, s8, v233
	s_setprio 1
	ds_read_b128 v[194:197], v230
	ds_read_b128 v[198:201], v230 offset:4096
	ds_read_b128 v[202:205], v230 offset:8192
	ds_read_b128 v[206:209], v230 offset:12288
	ds_read_b128 v[210:213], v247
	ds_read_b128 v[214:217], v247 offset:4096
	s_waitcnt lgkmcnt(5)
	v_mfma_f32_16x16x32_bf16 v[130:133], v[194:197], v[162:165], 0
	v_mfma_f32_16x16x32_bf16 v[134:137], v[194:197], v[178:181], 0
	ds_read_b128 v[194:197], v247 offset:8192
	s_waitcnt lgkmcnt(5)
	v_mfma_f32_16x16x32_bf16 v[138:141], v[198:201], v[162:165], 0
	v_mfma_f32_16x16x32_bf16 v[142:145], v[198:201], v[178:181], 0
	ds_read_b128 v[198:201], v247 offset:12288
	s_waitcnt lgkmcnt(5)
	v_mfma_f32_16x16x32_bf16 v[146:149], v[202:205], v[162:165], 0
	v_mfma_f32_16x16x32_bf16 v[150:153], v[202:205], v[178:181], 0
	ds_read_b128 v[202:205], v230 offset:128
	s_waitcnt lgkmcnt(5)
	v_mfma_f32_16x16x32_bf16 v[154:157], v[206:209], v[162:165], 0
	v_mfma_f32_16x16x32_bf16 v[158:161], v[206:209], v[178:181], 0
	ds_read_b128 v[206:209], v230 offset:4224
	s_waitcnt lgkmcnt(5)
	v_mfma_f32_16x16x32_bf16 v[130:133], v[210:213], v[166:169], v[130:133]
	v_mfma_f32_16x16x32_bf16 v[134:137], v[210:213], v[182:185], v[134:137]
	ds_read_b128 v[210:213], v230 offset:8320
	s_waitcnt lgkmcnt(5)
	v_mfma_f32_16x16x32_bf16 v[138:141], v[214:217], v[166:169], v[138:141]
	v_mfma_f32_16x16x32_bf16 v[142:145], v[214:217], v[182:185], v[142:145]
	ds_read_b128 v[214:217], v230 offset:12416
	s_waitcnt lgkmcnt(5)
	v_mfma_f32_16x16x32_bf16 v[146:149], v[194:197], v[166:169], v[146:149]
	v_mfma_f32_16x16x32_bf16 v[150:153], v[194:197], v[182:185], v[150:153]
	ds_read_b128 v[194:197], v247 offset:128
	s_waitcnt lgkmcnt(5)
	v_mfma_f32_16x16x32_bf16 v[154:157], v[198:201], v[166:169], v[154:157]
	v_mfma_f32_16x16x32_bf16 v[158:161], v[198:201], v[182:185], v[158:161]
	ds_read_b128 v[198:201], v247 offset:4224
	s_waitcnt lgkmcnt(5)
; __device__ __forceinline__ int crow(int r, int hi) { return (r & 3) + 8 * (r >> 2) + 4 * hi; }
; __device__ __forceinline__ int crow(int r, int hi) { return (r & 3) + 8 * (r >> 2) + 4 * hi; }
; __device__ __forceinline__ void partialSM(f32x16& p0, f32x16& p1, float& m_reg, float& mn, float& alpha) {
;   constexpr float C = SCALE * 1.4426950408889634f;
;   float pmax = p0[0]; for (int r = 1; r < 16; ++r) pmax = fmaxf(pmax, p0[r]); for (int r = 0; r < 16; ++r) pmax = fmaxf(pmax, p1[r]);
;   { auto rr = __builtin_amdgcn_permlane32_swap(__float_as_uint(pmax), __float_as_uint(pmax), false, false);
;     pmax = fmaxf(__uint_as_float(rr[0]), __uint_as_float(rr[1])); }
;   if (__builtin_expect(__all(pmax - m_reg <= THR / SCALE), 1)) { mn = m_reg; alpha = 1.f; }
;   else { mn = fmaxf(m_reg, pmax); alpha = __builtin_amdgcn_exp2f((m_reg - mn) * C); m_reg = mn; }
; __device__ __forceinline__ void attn_body256(const bf16_t* __restrict__ Qb, const bf16_t* __restrict__ Kh, const bf16_t* __restrict__ Vh,
;                                              bf16_t* Ob, int seq, unsigned char* lds, float lam, int MODE, bf16_t* Ab, const float* wsub) {
;     ...
;     if (__any(alpha < 1.f)) { if (hi == 0) al_l[r32] = alpha; asm volatile("s_waitcnt lgkmcnt(0)" ::: "memory");
; #pragma unroll
;       for (int r = 0; r < 16; ++r) { const float a = al_l[crow(r, hi)];
; #pragma unroll
;         for (int d = 0; d < 8; ++d) o[d][r] *= a; } }
	v_mfma_f32_16x16x32_bf16 v[130:133], v[202:205], v[170:173], v[130:133]
	v_mfma_f32_16x16x32_bf16 v[134:137], v[202:205], v[186:189], v[134:137]
	ds_read_b128 v[202:205], v247 offset:8320
	s_waitcnt lgkmcnt(5)
	v_mfma_f32_16x16x32_bf16 v[138:141], v[206:209], v[170:173], v[138:141]
	v_mfma_f32_16x16x32_bf16 v[142:145], v[206:209], v[186:189], v[142:145]
	ds_read_b128 v[206:209], v247 offset:12416
	s_waitcnt lgkmcnt(5)
	v_mfma_f32_16x16x32_bf16 v[146:149], v[210:213], v[170:173], v[146:149]
	v_mfma_f32_16x16x32_bf16 v[150:153], v[210:213], v[186:189], v[150:153]
	s_waitcnt lgkmcnt(4)
	v_mfma_f32_16x16x32_bf16 v[154:157], v[214:217], v[170:173], v[154:157]
	v_mfma_f32_16x16x32_bf16 v[158:161], v[214:217], v[186:189], v[158:161]
	s_waitcnt lgkmcnt(3)
	v_mfma_f32_16x16x32_bf16 v[130:133], v[194:197], v[174:177], v[130:133]
	v_mfma_f32_16x16x32_bf16 v[134:137], v[194:197], v[190:193], v[134:137]
	s_waitcnt lgkmcnt(2)
	v_mfma_f32_16x16x32_bf16 v[138:141], v[198:201], v[174:177], v[138:141]
	v_mfma_f32_16x16x32_bf16 v[142:145], v[198:201], v[190:193], v[142:145]
	s_waitcnt lgkmcnt(1)
	v_mfma_f32_16x16x32_bf16 v[146:149], v[202:205], v[174:177], v[146:149]
	v_mfma_f32_16x16x32_bf16 v[150:153], v[202:205], v[190:193], v[150:153]
	s_waitcnt lgkmcnt(0)
	v_mfma_f32_16x16x32_bf16 v[154:157], v[206:209], v[174:177], v[154:157]
	v_mfma_f32_16x16x32_bf16 v[158:161], v[206:209], v[190:193], v[158:161]
	s_setprio 0
	s_nop 6
	v_max3_f32 v194, v130, v131, v132
	v_max3_f32 v194, v194, v133, v138
	v_max3_f32 v194, v194, v139, v140
	v_max3_f32 v194, v194, v141, v146
	v_max3_f32 v194, v194, v147, v148
	v_max3_f32 v194, v194, v149, v154
	v_max3_f32 v194, v194, v155, v156
	v_max_f32_e32 v194, v194, v157
	v_max3_f32 v195, v134, v135, v136
	v_max3_f32 v195, v195, v137, v142
	v_max3_f32 v195, v195, v143, v144
	v_max3_f32 v195, v195, v145, v150
	v_max3_f32 v195, v195, v151, v152
	v_max3_f32 v195, v195, v153, v158
	v_max3_f32 v195, v195, v159, v160
	v_max_f32_e32 v195, v195, v161
	v_mov_b32_e32 v196, v194
	v_mov_b32_e32 v197, v195
	s_nop 1
	v_permlane32_swap_b32_e32 v194, v196
	v_permlane32_swap_b32_e32 v195, v197
	v_max_f32_e32 v194, v194, v196
	v_max_f32_e32 v195, v195, v197
	v_mov_b32_e32 v196, v194
	v_mov_b32_e32 v197, v195
	s_nop 1
	v_permlane16_swap_b32_e32 v194, v196
	v_permlane16_swap_b32_e32 v195, v197
	v_max_f32_e32 v194, v194, v196
	v_max_f32_e32 v195, v195, v197
	v_sub_f32_e32 v196, v194, v249
	v_sub_f32_e32 v197, v195, v246
	v_max_f32_e32 v196, v196, v197
	v_cmp_ge_f32_e32 vcc, 0x42b504f3, v196
	v_max_f32_e32 v198, v249, v194
	v_max_f32_e32 v199, v246, v195
	v_sub_f32_e32 v196, v249, v198
	v_sub_f32_e32 v197, v246, v199
	v_mul_f32_e32 v196, 0x3e0293ee, v196
	v_mul_f32_e32 v197, 0x3e0293ee, v197
	v_exp_f32_e32 v196, v196
	v_exp_f32_e32 v197, v197
	s_cmp_eq_u64 vcc, exec
	s_cselect_b64 s[8:9], -1, 0
	v_cndmask_b32_e64 v236, v196, 1.0, s[8:9]
	v_cndmask_b32_e64 v240, v197, 1.0, s[8:9]
	v_cndmask_b32_e64 v249, v198, v249, s[8:9]
	v_cndmask_b32_e64 v246, v199, v246, s[8:9]
	s_cbranch_scc1 .Lat_x_noresc
	v_pk_mul_f32 v[2:3], v[2:3], v[236:237] op_sel_hi:[1,0]
	v_pk_mul_f32 v[4:5], v[4:5], v[236:237] op_sel_hi:[1,0]
	v_pk_mul_f32 v[6:7], v[6:7], v[240:241] op_sel_hi:[1,0]
	v_pk_mul_f32 v[8:9], v[8:9], v[240:241] op_sel_hi:[1,0]
	v_pk_mul_f32 v[10:11], v[10:11], v[236:237] op_sel_hi:[1,0]
	v_pk_mul_f32 v[12:13], v[12:13], v[236:237] op_sel_hi:[1,0]
	v_pk_mul_f32 v[14:15], v[14:15], v[240:241] op_sel_hi:[1,0]
	v_pk_mul_f32 v[16:17], v[16:17], v[240:241] op_sel_hi:[1,0]
	v_pk_mul_f32 v[114:115], v[114:115], v[236:237] op_sel_hi:[1,0]
	v_pk_mul_f32 v[116:117], v[116:117], v[236:237] op_sel_hi:[1,0]
	v_pk_mul_f32 v[118:119], v[118:119], v[240:241] op_sel_hi:[1,0]
	v_pk_mul_f32 v[120:121], v[120:121], v[240:241] op_sel_hi:[1,0]
	v_pk_mul_f32 v[122:123], v[122:123], v[236:237] op_sel_hi:[1,0]
	v_pk_mul_f32 v[124:125], v[124:125], v[236:237] op_sel_hi:[1,0]
	v_pk_mul_f32 v[126:127], v[126:127], v[240:241] op_sel_hi:[1,0]
	v_pk_mul_f32 v[128:129], v[128:129], v[240:241] op_sel_hi:[1,0]
	v_pk_mul_f32 v[98:99], v[98:99], v[236:237] op_sel_hi:[1,0]
	v_pk_mul_f32 v[100:101], v[100:101], v[236:237] op_sel_hi:[1,0]
	v_pk_mul_f32 v[102:103], v[102:103], v[240:241] op_sel_hi:[1,0]
	v_pk_mul_f32 v[104:105], v[104:105], v[240:241] op_sel_hi:[1,0]
	v_pk_mul_f32 v[106:107], v[106:107], v[236:237] op_sel_hi:[1,0]
	v_pk_mul_f32 v[108:109], v[108:109], v[236:237] op_sel_hi:[1,0]
	v_pk_mul_f32 v[110:111], v[110:111], v[240:241] op_sel_hi:[1,0]
	v_pk_mul_f32 v[112:113], v[112:113], v[240:241] op_sel_hi:[1,0]
	v_pk_mul_f32 v[82:83], v[82:83], v[236:237] op_sel_hi:[1,0]
	v_pk_mul_f32 v[84:85], v[84:85], v[236:237] op_sel_hi:[1,0]
	v_pk_mul_f32 v[86:87], v[86:87], v[240:241] op_sel_hi:[1,0]
	v_pk_mul_f32 v[88:89], v[88:89], v[240:241] op_sel_hi:[1,0]
	v_pk_mul_f32 v[90:91], v[90:91], v[236:237] op_sel_hi:[1,0]
	v_pk_mul_f32 v[92:93], v[92:93], v[236:237] op_sel_hi:[1,0]
	v_pk_mul_f32 v[94:95], v[94:95], v[240:241] op_sel_hi:[1,0]
	v_pk_mul_f32 v[96:97], v[96:97], v[240:241] op_sel_hi:[1,0]
	v_pk_mul_f32 v[66:67], v[66:67], v[236:237] op_sel_hi:[1,0]
	v_pk_mul_f32 v[68:69], v[68:69], v[236:237] op_sel_hi:[1,0]
	v_pk_mul_f32 v[70:71], v[70:71], v[240:241] op_sel_hi:[1,0]
	v_pk_mul_f32 v[72:73], v[72:73], v[240:241] op_sel_hi:[1,0]
	v_pk_mul_f32 v[74:75], v[74:75], v[236:237] op_sel_hi:[1,0]
	v_pk_mul_f32 v[76:77], v[76:77], v[236:237] op_sel_hi:[1,0]
	v_pk_mul_f32 v[78:79], v[78:79], v[240:241] op_sel_hi:[1,0]
	v_pk_mul_f32 v[80:81], v[80:81], v[240:241] op_sel_hi:[1,0]
	v_pk_mul_f32 v[50:51], v[50:51], v[236:237] op_sel_hi:[1,0]
	v_pk_mul_f32 v[52:53], v[52:53], v[236:237] op_sel_hi:[1,0]
	v_pk_mul_f32 v[54:55], v[54:55], v[240:241] op_sel_hi:[1,0]
	v_pk_mul_f32 v[56:57], v[56:57], v[240:241] op_sel_hi:[1,0]
	v_pk_mul_f32 v[58:59], v[58:59], v[236:237] op_sel_hi:[1,0]
	v_pk_mul_f32 v[60:61], v[60:61], v[236:237] op_sel_hi:[1,0]
	v_pk_mul_f32 v[62:63], v[62:63], v[240:241] op_sel_hi:[1,0]
	v_pk_mul_f32 v[64:65], v[64:65], v[240:241] op_sel_hi:[1,0]
	v_pk_mul_f32 v[34:35], v[34:35], v[236:237] op_sel_hi:[1,0]
	v_pk_mul_f32 v[36:37], v[36:37], v[236:237] op_sel_hi:[1,0]
	v_pk_mul_f32 v[38:39], v[38:39], v[240:241] op_sel_hi:[1,0]
	v_pk_mul_f32 v[40:41], v[40:41], v[240:241] op_sel_hi:[1,0]
	v_pk_mul_f32 v[42:43], v[42:43], v[236:237] op_sel_hi:[1,0]
	v_pk_mul_f32 v[44:45], v[44:45], v[236:237] op_sel_hi:[1,0]
	v_pk_mul_f32 v[46:47], v[46:47], v[240:241] op_sel_hi:[1,0]
	v_pk_mul_f32 v[48:49], v[48:49], v[240:241] op_sel_hi:[1,0]
	v_pk_mul_f32 v[18:19], v[18:19], v[236:237] op_sel_hi:[1,0]
	v_pk_mul_f32 v[20:21], v[20:21], v[236:237] op_sel_hi:[1,0]
	v_pk_mul_f32 v[22:23], v[22:23], v[240:241] op_sel_hi:[1,0]
	v_pk_mul_f32 v[24:25], v[24:25], v[240:241] op_sel_hi:[1,0]
	v_pk_mul_f32 v[26:27], v[26:27], v[236:237] op_sel_hi:[1,0]
	v_pk_mul_f32 v[28:29], v[28:29], v[236:237] op_sel_hi:[1,0]
	v_pk_mul_f32 v[30:31], v[30:31], v[240:241] op_sel_hi:[1,0]
	v_pk_mul_f32 v[32:33], v[32:33], v[240:241] op_sel_hi:[1,0]
; #define SBAR() __builtin_amdgcn_sched_barrier(0)
; __device__ __forceinline__ void partialSM(f32x16& p0, f32x16& p1, float& m_reg, float& mn, float& alpha) {
;     ...
;   for (int r = 0; r < 16; ++r) p0[r] = fmaf(p0[r], C, mnC); for (int r = 0; r < 16; ++r) p1[r] = fmaf(p1[r], C, mnC);
;   for (int r = 0; r < 16; ++r) p0[r] = __builtin_amdgcn_exp2f(p0[r]);
; }
; __device__ __forceinline__ void finishSM(f32x16& p0, f32x16& p1, float alpha, float& l_reg, bf16x8& pa0, bf16x8& pa1, bf16x8& pa2, bf16x8& pa3) {
;   for (int r = 0; r < 16; ++r) p1[r] = __builtin_amdgcn_exp2f(p1[r]);
;   float ps = 0; for (int r = 0; r < 16; ++r) ps += p0[r]; for (int r = 0; r < 16; ++r) ps += p1[r];
;   { auto rr = __builtin_amdgcn_permlane32_swap(__float_as_uint(ps), __float_as_uint(ps), false, false);
;     ps = __uint_as_float(rr[0]) + __uint_as_float(rr[1]); }
;   l_reg = l_reg * alpha + ps;
;     ...
;   PK4(p0, 0, pa0); PK4(p0, 8, pa1); PK4(p1, 0, pa2); PK4(p1, 8, pa3);
;     ...
; }
; template <int B> __device__ __forceinline__ void pv_reads(VFrag& f, int vb) {
;   constexpr int base = (B >> 2) * 16384 + (B & 3) * 512;
;   f.l0 = tr_read<base + 0 * 4096>(vb); f.h0 = tr_read<base + 0 * 4096 + 2048>(vb); f.l1 = tr_read<base + 1 * 4096>(vb); f.h1 = tr_read<base + 1 * 4096 + 2048>(vb);
;   f.l2 = tr_read<base + 2 * 4096>(vb); f.h2 = tr_read<base + 2 * 4096 + 2048>(vb); f.l3 = tr_read<base + 3 * 4096>(vb); f.h3 = tr_read<base + 3 * 4096 + 2048>(vb);
; }
; __device__ __forceinline__ void pv_mma(f32x16& od, const VFrag& f, bf16x8 pa0, bf16x8 pa1, bf16x8 pa2, bf16x8 pa3) {
;     ...
;   od = __builtin_amdgcn_mfma_f32_32x32x16_bf16(pa0, PKV(f.l0, f.h0), od, 0, 0, 0);
;   od = __builtin_amdgcn_mfma_f32_32x32x16_bf16(pa1, PKV(f.l1, f.h1), od, 0, 0, 0);
;   od = __builtin_amdgcn_mfma_f32_32x32x16_bf16(pa2, PKV(f.l2, f.h2), od, 0, 0, 0);
;   od = __builtin_amdgcn_mfma_f32_32x32x16_bf16(pa3, PKV(f.l3, f.h3), od, 0, 0, 0);
;     ...
; }
; __device__ __forceinline__ void pv_all(f32x16* o, int vb, bf16x8 pa0, bf16x8 pa1, bf16x8 pa2, bf16x8 pa3) {
;   VFrag fc, fn;
;   pv_reads<0>(fc, vb);
;   PV_STEP(0); PV_STEP(1); PV_STEP(2); PV_STEP(3); PV_STEP(4); PV_STEP(5); PV_STEP(6);
;   asm volatile("s_waitcnt lgkmcnt(0)" ::: "memory"); SBAR(); pv_mma(o[7], fc, pa0, pa1, pa2, pa3);
.Lat_x_noresc:
	v_mul_f32_e32 v198, 0xbe0293ee, v249
	v_mul_f32_e32 v199, 0xbe0293ee, v246
	v_fmamk_f32 v130, v130, 0x3e0293ee, v198
	v_fmamk_f32 v131, v131, 0x3e0293ee, v198
	v_fmamk_f32 v132, v132, 0x3e0293ee, v198
	v_fmamk_f32 v133, v133, 0x3e0293ee, v198
	v_fmamk_f32 v134, v134, 0x3e0293ee, v199
	v_fmamk_f32 v135, v135, 0x3e0293ee, v199
	v_fmamk_f32 v136, v136, 0x3e0293ee, v199
	v_fmamk_f32 v137, v137, 0x3e0293ee, v199
	v_fmamk_f32 v138, v138, 0x3e0293ee, v198
	v_fmamk_f32 v139, v139, 0x3e0293ee, v198
	v_fmamk_f32 v140, v140, 0x3e0293ee, v198
	v_fmamk_f32 v141, v141, 0x3e0293ee, v198
	v_fmamk_f32 v142, v142, 0x3e0293ee, v199
	v_fmamk_f32 v143, v143, 0x3e0293ee, v199
	v_fmamk_f32 v144, v144, 0x3e0293ee, v199
	v_fmamk_f32 v145, v145, 0x3e0293ee, v199
	v_fmamk_f32 v146, v146, 0x3e0293ee, v198
	v_fmamk_f32 v147, v147, 0x3e0293ee, v198
	v_fmamk_f32 v148, v148, 0x3e0293ee, v198
	v_fmamk_f32 v149, v149, 0x3e0293ee, v198
	v_fmamk_f32 v150, v150, 0x3e0293ee, v199
	v_fmamk_f32 v151, v151, 0x3e0293ee, v199
	v_fmamk_f32 v152, v152, 0x3e0293ee, v199
	v_fmamk_f32 v153, v153, 0x3e0293ee, v199
	v_fmamk_f32 v154, v154, 0x3e0293ee, v198
	v_fmamk_f32 v155, v155, 0x3e0293ee, v198
	v_fmamk_f32 v156, v156, 0x3e0293ee, v198
	v_fmamk_f32 v157, v157, 0x3e0293ee, v198
	v_fmamk_f32 v158, v158, 0x3e0293ee, v199
	v_fmamk_f32 v159, v159, 0x3e0293ee, v199
	v_fmamk_f32 v160, v160, 0x3e0293ee, v199
	v_fmamk_f32 v161, v161, 0x3e0293ee, v199
	v_exp_f32_e32 v130, v130
	v_exp_f32_e32 v131, v131
	v_exp_f32_e32 v132, v132
	v_exp_f32_e32 v133, v133
	v_exp_f32_e32 v134, v134
	v_exp_f32_e32 v135, v135
	v_exp_f32_e32 v136, v136
	v_exp_f32_e32 v137, v137
	v_exp_f32_e32 v138, v138
	v_exp_f32_e32 v139, v139
	v_exp_f32_e32 v140, v140
	v_exp_f32_e32 v141, v141
	v_exp_f32_e32 v142, v142
	v_exp_f32_e32 v143, v143
	v_exp_f32_e32 v144, v144
	v_exp_f32_e32 v145, v145
	v_exp_f32_e32 v146, v146
	v_exp_f32_e32 v147, v147
	v_exp_f32_e32 v148, v148
	v_exp_f32_e32 v149, v149
	v_exp_f32_e32 v150, v150
	v_exp_f32_e32 v151, v151
	v_exp_f32_e32 v152, v152
	v_exp_f32_e32 v153, v153
	v_exp_f32_e32 v154, v154
	v_exp_f32_e32 v155, v155
	v_exp_f32_e32 v156, v156
	v_exp_f32_e32 v157, v157
	v_exp_f32_e32 v158, v158
	v_exp_f32_e32 v159, v159
	v_exp_f32_e32 v160, v160
	v_exp_f32_e32 v161, v161
	v_add_f32_e32 v194, v130, v131
	v_add_f32_e32 v194, v194, v132
	v_add_f32_e32 v194, v194, v133
	v_add_f32_e32 v194, v194, v138
	v_add_f32_e32 v194, v194, v139
	v_add_f32_e32 v194, v194, v140
	v_add_f32_e32 v194, v194, v141
	v_add_f32_e32 v194, v194, v146
	v_add_f32_e32 v194, v194, v147
	v_add_f32_e32 v194, v194, v148
	v_add_f32_e32 v194, v194, v149
	v_add_f32_e32 v194, v194, v154
	v_add_f32_e32 v194, v194, v155
	v_add_f32_e32 v194, v194, v156
	v_add_f32_e32 v194, v194, v157
	v_add_f32_e32 v195, v134, v135
	v_add_f32_e32 v195, v195, v136
	v_add_f32_e32 v195, v195, v137
	v_add_f32_e32 v195, v195, v142
	v_add_f32_e32 v195, v195, v143
	v_add_f32_e32 v195, v195, v144
	v_add_f32_e32 v195, v195, v145
	v_add_f32_e32 v195, v195, v150
	v_add_f32_e32 v195, v195, v151
	v_add_f32_e32 v195, v195, v152
	v_add_f32_e32 v195, v195, v153
	v_add_f32_e32 v195, v195, v158
	v_add_f32_e32 v195, v195, v159
	v_add_f32_e32 v195, v195, v160
	v_add_f32_e32 v195, v195, v161
	v_fma_f32 v250, v250, v236, v194
	v_fma_f32 v234, v234, v240, v195
	v_cvt_pk_bf16_f32 v130, v130, v131
	v_cvt_pk_bf16_f32 v131, v132, v133
	v_cvt_pk_bf16_f32 v132, v138, v139
	v_cvt_pk_bf16_f32 v133, v140, v141
	v_cvt_pk_bf16_f32 v134, v134, v135
	v_cvt_pk_bf16_f32 v135, v136, v137
	v_cvt_pk_bf16_f32 v136, v142, v143
	v_cvt_pk_bf16_f32 v137, v144, v145
	v_cvt_pk_bf16_f32 v138, v146, v147
	v_cvt_pk_bf16_f32 v139, v148, v149
	v_cvt_pk_bf16_f32 v140, v154, v155
	v_cvt_pk_bf16_f32 v141, v156, v157
	v_cvt_pk_bf16_f32 v142, v150, v151
	v_cvt_pk_bf16_f32 v143, v152, v153
	v_cvt_pk_bf16_f32 v144, v158, v159
	v_cvt_pk_bf16_f32 v145, v160, v161
	v_add_u32_e32 v244, s98, v248
	ds_read_b64_tr_b16 v[146:147], v244
	ds_read_b64_tr_b16 v[148:149], v244 offset:4096
	ds_read_b64_tr_b16 v[150:151], v244 offset:8192
	ds_read_b64_tr_b16 v[152:153], v244 offset:12288
	ds_read_b64_tr_b16 v[154:155], v244 offset:256
	ds_read_b64_tr_b16 v[156:157], v244 offset:4352
	ds_read_b64_tr_b16 v[158:159], v244 offset:8448
	ds_read_b64_tr_b16 v[160:161], v244 offset:12544
	ds_read_b64_tr_b16 v[194:195], v244 offset:512
	ds_read_b64_tr_b16 v[196:197], v244 offset:4608
	ds_read_b64_tr_b16 v[198:199], v244 offset:8704
	ds_read_b64_tr_b16 v[200:201], v244 offset:12800
	s_waitcnt lgkmcnt(8)
	v_mfma_f32_16x16x32_bf16 v[2:5], v[146:149], v[130:133], v[2:5]
	v_mfma_f32_16x16x32_bf16 v[6:9], v[146:149], v[134:137], v[6:9]
	v_mfma_f32_16x16x32_bf16 v[2:5], v[150:153], v[138:141], v[2:5]
	v_mfma_f32_16x16x32_bf16 v[6:9], v[150:153], v[142:145], v[6:9]
	ds_read_b64_tr_b16 v[146:147], v244 offset:768
	ds_read_b64_tr_b16 v[148:149], v244 offset:4864
	ds_read_b64_tr_b16 v[150:151], v244 offset:8960
	ds_read_b64_tr_b16 v[152:153], v244 offset:13056
	s_waitcnt lgkmcnt(8)
	v_mfma_f32_16x16x32_bf16 v[10:13], v[154:157], v[130:133], v[10:13]
	v_mfma_f32_16x16x32_bf16 v[14:17], v[154:157], v[134:137], v[14:17]
	v_mfma_f32_16x16x32_bf16 v[10:13], v[158:161], v[138:141], v[10:13]
	v_mfma_f32_16x16x32_bf16 v[14:17], v[158:161], v[142:145], v[14:17]
	ds_read_b64_tr_b16 v[154:155], v244 offset:1024
	ds_read_b64_tr_b16 v[156:157], v244 offset:5120
	ds_read_b64_tr_b16 v[158:159], v244 offset:9216
	ds_read_b64_tr_b16 v[160:161], v244 offset:13312
	s_waitcnt lgkmcnt(8)
; #define SBAR() __builtin_amdgcn_sched_barrier(0)
; #define PV_STEP(B) do { pv_reads<(B) + 1>(fn, vb); asm volatile("s_waitcnt lgkmcnt(8)" ::: "memory"); SBAR(); pv_mma(o[B], fc, pa0, pa1, pa2, pa3); SBAR(); fc = fn; } while (0)
; template <int B> __device__ __forceinline__ void pv_reads(VFrag& f, int vb) {
;   constexpr int base = (B >> 2) * 16384 + (B & 3) * 512;
;   f.l0 = tr_read<base + 0 * 4096>(vb); f.h0 = tr_read<base + 0 * 4096 + 2048>(vb); f.l1 = tr_read<base + 1 * 4096>(vb); f.h1 = tr_read<base + 1 * 4096 + 2048>(vb);
;   f.l2 = tr_read<base + 2 * 4096>(vb); f.h2 = tr_read<base + 2 * 4096 + 2048>(vb); f.l3 = tr_read<base + 3 * 4096>(vb); f.h3 = tr_read<base + 3 * 4096 + 2048>(vb);
; }
; __device__ __forceinline__ void pv_mma(f32x16& od, const VFrag& f, bf16x8 pa0, bf16x8 pa1, bf16x8 pa2, bf16x8 pa3) {
;     ...
;   od = __builtin_amdgcn_mfma_f32_32x32x16_bf16(pa0, PKV(f.l0, f.h0), od, 0, 0, 0);
;   od = __builtin_amdgcn_mfma_f32_32x32x16_bf16(pa1, PKV(f.l1, f.h1), od, 0, 0, 0);
;   od = __builtin_amdgcn_mfma_f32_32x32x16_bf16(pa2, PKV(f.l2, f.h2), od, 0, 0, 0);
;   od = __builtin_amdgcn_mfma_f32_32x32x16_bf16(pa3, PKV(f.l3, f.h3), od, 0, 0, 0);
;     ...
; }
; __device__ __forceinline__ void pv_all(f32x16* o, int vb, bf16x8 pa0, bf16x8 pa1, bf16x8 pa2, bf16x8 pa3) {
;   VFrag fc, fn;
;   pv_reads<0>(fc, vb);
;   PV_STEP(0); PV_STEP(1); PV_STEP(2); PV_STEP(3); PV_STEP(4); PV_STEP(5); PV_STEP(6);
;   asm volatile("s_waitcnt lgkmcnt(0)" ::: "memory"); SBAR(); pv_mma(o[7], fc, pa0, pa1, pa2, pa3);
; }
; __device__ __forceinline__ void attn_body256(const bf16_t* __restrict__ Qb, const bf16_t* __restrict__ Kh, const bf16_t* __restrict__ Vh,
;                                              bf16_t* Ob, int seq, unsigned char* lds, float lam, int MODE, bf16_t* Ab, const float* wsub) {
;     ...
;     asm volatile("s_waitcnt vmcnt(0)" ::: "memory"); __syncthreads();
	v_mfma_f32_16x16x32_bf16 v[114:117], v[194:197], v[130:133], v[114:117]
	v_mfma_f32_16x16x32_bf16 v[118:121], v[194:197], v[134:137], v[118:121]
	v_mfma_f32_16x16x32_bf16 v[114:117], v[198:201], v[138:141], v[114:117]
	v_mfma_f32_16x16x32_bf16 v[118:121], v[198:201], v[142:145], v[118:121]
	ds_read_b64_tr_b16 v[194:195], v244 offset:1280
	ds_read_b64_tr_b16 v[196:197], v244 offset:5376
	ds_read_b64_tr_b16 v[198:199], v244 offset:9472
	ds_read_b64_tr_b16 v[200:201], v244 offset:13568
	s_waitcnt lgkmcnt(8)
	v_mfma_f32_16x16x32_bf16 v[122:125], v[146:149], v[130:133], v[122:125]
	v_mfma_f32_16x16x32_bf16 v[126:129], v[146:149], v[134:137], v[126:129]
	v_mfma_f32_16x16x32_bf16 v[122:125], v[150:153], v[138:141], v[122:125]
	v_mfma_f32_16x16x32_bf16 v[126:129], v[150:153], v[142:145], v[126:129]
	ds_read_b64_tr_b16 v[146:147], v244 offset:1536
	ds_read_b64_tr_b16 v[148:149], v244 offset:5632
	ds_read_b64_tr_b16 v[150:151], v244 offset:9728
	ds_read_b64_tr_b16 v[152:153], v244 offset:13824
	s_waitcnt lgkmcnt(8)
	v_mfma_f32_16x16x32_bf16 v[98:101], v[154:157], v[130:133], v[98:101]
	v_mfma_f32_16x16x32_bf16 v[102:105], v[154:157], v[134:137], v[102:105]
	v_mfma_f32_16x16x32_bf16 v[98:101], v[158:161], v[138:141], v[98:101]
	v_mfma_f32_16x16x32_bf16 v[102:105], v[158:161], v[142:145], v[102:105]
	ds_read_b64_tr_b16 v[154:155], v244 offset:1792
	ds_read_b64_tr_b16 v[156:157], v244 offset:5888
	ds_read_b64_tr_b16 v[158:159], v244 offset:9984
	ds_read_b64_tr_b16 v[160:161], v244 offset:14080
	s_waitcnt lgkmcnt(8)
	v_mfma_f32_16x16x32_bf16 v[106:109], v[194:197], v[130:133], v[106:109]
	v_mfma_f32_16x16x32_bf16 v[110:113], v[194:197], v[134:137], v[110:113]
	v_mfma_f32_16x16x32_bf16 v[106:109], v[198:201], v[138:141], v[106:109]
	v_mfma_f32_16x16x32_bf16 v[110:113], v[198:201], v[142:145], v[110:113]
	ds_read_b64_tr_b16 v[194:195], v244 offset:16384
	ds_read_b64_tr_b16 v[196:197], v244 offset:20480
	ds_read_b64_tr_b16 v[198:199], v244 offset:24576
	ds_read_b64_tr_b16 v[200:201], v244 offset:28672
	s_waitcnt lgkmcnt(8)
	v_mfma_f32_16x16x32_bf16 v[82:85], v[146:149], v[130:133], v[82:85]
	v_mfma_f32_16x16x32_bf16 v[86:89], v[146:149], v[134:137], v[86:89]
	v_mfma_f32_16x16x32_bf16 v[82:85], v[150:153], v[138:141], v[82:85]
	v_mfma_f32_16x16x32_bf16 v[86:89], v[150:153], v[142:145], v[86:89]
	ds_read_b64_tr_b16 v[146:147], v244 offset:16640
	ds_read_b64_tr_b16 v[148:149], v244 offset:20736
	ds_read_b64_tr_b16 v[150:151], v244 offset:24832
	ds_read_b64_tr_b16 v[152:153], v244 offset:28928
	s_waitcnt lgkmcnt(8)
	v_mfma_f32_16x16x32_bf16 v[90:93], v[154:157], v[130:133], v[90:93]
	v_mfma_f32_16x16x32_bf16 v[94:97], v[154:157], v[134:137], v[94:97]
	v_mfma_f32_16x16x32_bf16 v[90:93], v[158:161], v[138:141], v[90:93]
	v_mfma_f32_16x16x32_bf16 v[94:97], v[158:161], v[142:145], v[94:97]
	ds_read_b64_tr_b16 v[154:155], v244 offset:16896
	ds_read_b64_tr_b16 v[156:157], v244 offset:20992
	ds_read_b64_tr_b16 v[158:159], v244 offset:25088
	ds_read_b64_tr_b16 v[160:161], v244 offset:29184
	s_waitcnt lgkmcnt(8)
	v_mfma_f32_16x16x32_bf16 v[66:69], v[194:197], v[130:133], v[66:69]
	v_mfma_f32_16x16x32_bf16 v[70:73], v[194:197], v[134:137], v[70:73]
	v_mfma_f32_16x16x32_bf16 v[66:69], v[198:201], v[138:141], v[66:69]
	v_mfma_f32_16x16x32_bf16 v[70:73], v[198:201], v[142:145], v[70:73]
	ds_read_b64_tr_b16 v[194:195], v244 offset:17152
	ds_read_b64_tr_b16 v[196:197], v244 offset:21248
	ds_read_b64_tr_b16 v[198:199], v244 offset:25344
	ds_read_b64_tr_b16 v[200:201], v244 offset:29440
	s_waitcnt lgkmcnt(8)
	v_mfma_f32_16x16x32_bf16 v[74:77], v[146:149], v[130:133], v[74:77]
	v_mfma_f32_16x16x32_bf16 v[78:81], v[146:149], v[134:137], v[78:81]
	v_mfma_f32_16x16x32_bf16 v[74:77], v[150:153], v[138:141], v[74:77]
	v_mfma_f32_16x16x32_bf16 v[78:81], v[150:153], v[142:145], v[78:81]
	ds_read_b64_tr_b16 v[146:147], v244 offset:17408
	ds_read_b64_tr_b16 v[148:149], v244 offset:21504
	ds_read_b64_tr_b16 v[150:151], v244 offset:25600
	ds_read_b64_tr_b16 v[152:153], v244 offset:29696
	s_waitcnt lgkmcnt(8)
	v_mfma_f32_16x16x32_bf16 v[50:53], v[154:157], v[130:133], v[50:53]
	v_mfma_f32_16x16x32_bf16 v[54:57], v[154:157], v[134:137], v[54:57]
	v_mfma_f32_16x16x32_bf16 v[50:53], v[158:161], v[138:141], v[50:53]
	v_mfma_f32_16x16x32_bf16 v[54:57], v[158:161], v[142:145], v[54:57]
	ds_read_b64_tr_b16 v[154:155], v244 offset:17664
	ds_read_b64_tr_b16 v[156:157], v244 offset:21760
	ds_read_b64_tr_b16 v[158:159], v244 offset:25856
	ds_read_b64_tr_b16 v[160:161], v244 offset:29952
	s_waitcnt lgkmcnt(8)
	v_mfma_f32_16x16x32_bf16 v[58:61], v[194:197], v[130:133], v[58:61]
	v_mfma_f32_16x16x32_bf16 v[62:65], v[194:197], v[134:137], v[62:65]
	v_mfma_f32_16x16x32_bf16 v[58:61], v[198:201], v[138:141], v[58:61]
	v_mfma_f32_16x16x32_bf16 v[62:65], v[198:201], v[142:145], v[62:65]
	ds_read_b64_tr_b16 v[194:195], v244 offset:17920
	ds_read_b64_tr_b16 v[196:197], v244 offset:22016
	ds_read_b64_tr_b16 v[198:199], v244 offset:26112
	ds_read_b64_tr_b16 v[200:201], v244 offset:30208
	s_waitcnt lgkmcnt(8)
	v_mfma_f32_16x16x32_bf16 v[34:37], v[146:149], v[130:133], v[34:37]
	v_mfma_f32_16x16x32_bf16 v[38:41], v[146:149], v[134:137], v[38:41]
	v_mfma_f32_16x16x32_bf16 v[34:37], v[150:153], v[138:141], v[34:37]
	v_mfma_f32_16x16x32_bf16 v[38:41], v[150:153], v[142:145], v[38:41]
	ds_read_b64_tr_b16 v[146:147], v244 offset:18176
	ds_read_b64_tr_b16 v[148:149], v244 offset:22272
	ds_read_b64_tr_b16 v[150:151], v244 offset:26368
	ds_read_b64_tr_b16 v[152:153], v244 offset:30464
	s_waitcnt lgkmcnt(8)
	v_mfma_f32_16x16x32_bf16 v[42:45], v[154:157], v[130:133], v[42:45]
	v_mfma_f32_16x16x32_bf16 v[46:49], v[154:157], v[134:137], v[46:49]
	v_mfma_f32_16x16x32_bf16 v[42:45], v[158:161], v[138:141], v[42:45]
	v_mfma_f32_16x16x32_bf16 v[46:49], v[158:161], v[142:145], v[46:49]
	s_waitcnt lgkmcnt(4)
	v_mfma_f32_16x16x32_bf16 v[18:21], v[194:197], v[130:133], v[18:21]
	v_mfma_f32_16x16x32_bf16 v[22:25], v[194:197], v[134:137], v[22:25]
	v_mfma_f32_16x16x32_bf16 v[18:21], v[198:201], v[138:141], v[18:21]
	v_mfma_f32_16x16x32_bf16 v[22:25], v[198:201], v[142:145], v[22:25]
	s_waitcnt lgkmcnt(0)
	v_mfma_f32_16x16x32_bf16 v[26:29], v[146:149], v[130:133], v[26:29]
	v_mfma_f32_16x16x32_bf16 v[30:33], v[146:149], v[134:137], v[30:33]
	v_mfma_f32_16x16x32_bf16 v[26:29], v[150:153], v[138:141], v[26:29]
	v_mfma_f32_16x16x32_bf16 v[30:33], v[150:153], v[142:145], v[30:33]
	s_waitcnt vmcnt(0)
	s_barrier
; template <int B> __device__ __forceinline__ void pv_reads(VFrag& f, int vb) {
;   constexpr int base = (B >> 2) * 16384 + (B & 3) * 512;
;   f.l0 = tr_read<base + 0 * 4096>(vb); f.h0 = tr_read<base + 0 * 4096 + 2048>(vb); f.l1 = tr_read<base + 1 * 4096>(vb); f.h1 = tr_read<base + 1 * 4096 + 2048>(vb);
;   f.l2 = tr_read<base + 2 * 4096>(vb); f.h2 = tr_read<base + 2 * 4096 + 2048>(vb); f.l3 = tr_read<base + 3 * 4096>(vb); f.h3 = tr_read<base + 3 * 4096 + 2048>(vb);
; }
; __device__ __forceinline__ void pv_mma(f32x16& od, const VFrag& f, bf16x8 pa0, bf16x8 pa1, bf16x8 pa2, bf16x8 pa3) {
;     ...
;   od = __builtin_amdgcn_mfma_f32_32x32x16_bf16(pa0, PKV(f.l0, f.h0), od, 0, 0, 0);
;   od = __builtin_amdgcn_mfma_f32_32x32x16_bf16(pa1, PKV(f.l1, f.h1), od, 0, 0, 0);
;   od = __builtin_amdgcn_mfma_f32_32x32x16_bf16(pa2, PKV(f.l2, f.h2), od, 0, 0, 0);
;   od = __builtin_amdgcn_mfma_f32_32x32x16_bf16(pa3, PKV(f.l3, f.h3), od, 0, 0, 0);
;     ...
; }
; __device__ __forceinline__ void attn_body256(const bf16_t* __restrict__ Qb, const bf16_t* __restrict__ Kh, const bf16_t* __restrict__ Vh,
;                                              bf16_t* Ob, int seq, unsigned char* lds, float lam, int MODE, bf16_t* Ab, const float* wsub) {
;     ...
;     asm volatile("s_waitcnt vmcnt(0)" ::: "memory"); __syncthreads();
;     if (j + 2 < NT) A2_DMA(j + 2, b);
;   }
	s_cmp_ge_u32 s13, s19
	s_cbranch_scc1 .Lat_x_nodma
	s_add_i32 s9, s22, s24
	v_lshl_add_u64 v[194:195], v[220:221], 0, s[14:15]
	s_mov_b32 m0, s9
	s_add_i32 s8, s21, s100
	global_load_lds_dwordx4 v[194:195], off
	v_lshl_add_u64 v[194:195], v[224:225], 0, s[14:15]
	s_add_i32 s16, s8, 0x4000
	v_lshl_add_u64 v[196:197], v[194:195], 0, s[54:55]
	s_mov_b32 m0, s8
	v_lshl_add_u64 v[194:195], v[194:195], 0, s[4:5]
	global_load_lds_dwordx4 v[196:197], off
	s_mov_b32 m0, s16
	s_nop 0
	global_load_lds_dwordx4 v[194:195], off
	v_lshl_add_u64 v[194:195], v[222:223], 0, s[14:15]
	s_add_i32 m0, s9, 0x2000
	s_nop 0
	global_load_lds_dwordx4 v[194:195], off
	v_lshl_add_u64 v[194:195], v[226:227], 0, s[14:15]
	v_lshl_add_u64 v[196:197], v[194:195], 0, s[54:55]
	s_add_i32 m0, s8, 0x2000
	v_lshl_add_u64 v[194:195], v[194:195], 0, s[4:5]
	global_load_lds_dwordx4 v[196:197], off
	s_add_i32 m0, s8, 0x6000
	s_nop 0
	global_load_lds_dwordx4 v[194:195], off
.Lat_x_nodma:
	s_mov_b32 s101, s98
	s_mov_b32 s98, s99
	s_mov_b32 s99, s100
	s_mov_b32 s100, s101
	s_add_u32 s14, s14, 0x40000
	s_addc_u32 s15, s15, 0
	s_add_i32 s13, s13, 1
	s_cmp_eq_u32 s23, s14
	s_cbranch_scc0 .Lat_x_top
	s_branch .Lat_epi
.Lat_y_top:
	v_add_u32_e32 v244, s100, v248
	ds_read_b64_tr_b16 v[146:147], v244
	ds_read_b64_tr_b16 v[148:149], v244 offset:4096
	ds_read_b64_tr_b16 v[150:151], v244 offset:8192
	ds_read_b64_tr_b16 v[152:153], v244 offset:12288
	ds_read_b64_tr_b16 v[154:155], v244 offset:256
	ds_read_b64_tr_b16 v[156:157], v244 offset:4352
	ds_read_b64_tr_b16 v[158:159], v244 offset:8448
	ds_read_b64_tr_b16 v[160:161], v244 offset:12544
	ds_read_b64_tr_b16 v[194:195], v244 offset:512
	ds_read_b64_tr_b16 v[196:197], v244 offset:4608
	ds_read_b64_tr_b16 v[198:199], v244 offset:8704
	ds_read_b64_tr_b16 v[200:201], v244 offset:12800
	s_waitcnt lgkmcnt(8)
	v_mfma_f32_16x16x32_bf16 v[2:5], v[146:149], v[130:133], v[2:5]
	v_mfma_f32_16x16x32_bf16 v[6:9], v[146:149], v[134:137], v[6:9]
	v_mfma_f32_16x16x32_bf16 v[2:5], v[150:153], v[138:141], v[2:5]
	v_mfma_f32_16x16x32_bf16 v[6:9], v[150:153], v[142:145], v[6:9]
	ds_read_b64_tr_b16 v[146:147], v244 offset:768
	ds_read_b64_tr_b16 v[148:149], v244 offset:4864
	ds_read_b64_tr_b16 v[150:151], v244 offset:8960
	ds_read_b64_tr_b16 v[152:153], v244 offset:13056
	s_waitcnt lgkmcnt(8)
	v_mfma_f32_16x16x32_bf16 v[10:13], v[154:157], v[130:133], v[10:13]
	v_mfma_f32_16x16x32_bf16 v[14:17], v[154:157], v[134:137], v[14:17]
	v_mfma_f32_16x16x32_bf16 v[10:13], v[158:161], v[138:141], v[10:13]
	v_mfma_f32_16x16x32_bf16 v[14:17], v[158:161], v[142:145], v[14:17]
	ds_read_b64_tr_b16 v[154:155], v244 offset:1024
	ds_read_b64_tr_b16 v[156:157], v244 offset:5120
	ds_read_b64_tr_b16 v[158:159], v244 offset:9216
	ds_read_b64_tr_b16 v[160:161], v244 offset:13312
	s_waitcnt lgkmcnt(8)
	v_mfma_f32_16x16x32_bf16 v[114:117], v[194:197], v[130:133], v[114:117]
	v_mfma_f32_16x16x32_bf16 v[118:121], v[194:197], v[134:137], v[118:121]
	v_mfma_f32_16x16x32_bf16 v[114:117], v[198:201], v[138:141], v[114:117]
	v_mfma_f32_16x16x32_bf16 v[118:121], v[198:201], v[142:145], v[118:121]
	ds_read_b64_tr_b16 v[194:195], v244 offset:1280
	ds_read_b64_tr_b16 v[196:197], v244 offset:5376
	ds_read_b64_tr_b16 v[198:199], v244 offset:9472
	ds_read_b64_tr_b16 v[200:201], v244 offset:13568
	s_waitcnt lgkmcnt(8)
	v_mfma_f32_16x16x32_bf16 v[122:125], v[146:149], v[130:133], v[122:125]
	v_mfma_f32_16x16x32_bf16 v[126:129], v[146:149], v[134:137], v[126:129]
	v_mfma_f32_16x16x32_bf16 v[122:125], v[150:153], v[138:141], v[122:125]
	v_mfma_f32_16x16x32_bf16 v[126:129], v[150:153], v[142:145], v[126:129]
	ds_read_b64_tr_b16 v[146:147], v244 offset:1536
	ds_read_b64_tr_b16 v[148:149], v244 offset:5632
	ds_read_b64_tr_b16 v[150:151], v244 offset:9728
	ds_read_b64_tr_b16 v[152:153], v244 offset:13824
	s_waitcnt lgkmcnt(8)
	v_mfma_f32_16x16x32_bf16 v[98:101], v[154:157], v[130:133], v[98:101]
	v_mfma_f32_16x16x32_bf16 v[102:105], v[154:157], v[134:137], v[102:105]
	v_mfma_f32_16x16x32_bf16 v[98:101], v[158:161], v[138:141], v[98:101]
	v_mfma_f32_16x16x32_bf16 v[102:105], v[158:161], v[142:145], v[102:105]
	ds_read_b64_tr_b16 v[154:155], v244 offset:1792
	ds_read_b64_tr_b16 v[156:157], v244 offset:5888
	ds_read_b64_tr_b16 v[158:159], v244 offset:9984
	ds_read_b64_tr_b16 v[160:161], v244 offset:14080
	s_waitcnt lgkmcnt(8)
	v_mfma_f32_16x16x32_bf16 v[106:109], v[194:197], v[130:133], v[106:109]
	v_mfma_f32_16x16x32_bf16 v[110:113], v[194:197], v[134:137], v[110:113]
	v_mfma_f32_16x16x32_bf16 v[106:109], v[198:201], v[138:141], v[106:109]
	v_mfma_f32_16x16x32_bf16 v[110:113], v[198:201], v[142:145], v[110:113]
	ds_read_b64_tr_b16 v[194:195], v244 offset:16384
	ds_read_b64_tr_b16 v[196:197], v244 offset:20480
	ds_read_b64_tr_b16 v[198:199], v244 offset:24576
	ds_read_b64_tr_b16 v[200:201], v244 offset:28672
	s_waitcnt lgkmcnt(8)
; #define SBAR() __builtin_amdgcn_sched_barrier(0)
; #define PV_STEP(B) do { pv_reads<(B) + 1>(fn, vb); asm volatile("s_waitcnt lgkmcnt(8)" ::: "memory"); SBAR(); pv_mma(o[B], fc, pa0, pa1, pa2, pa3); SBAR(); fc = fn; } while (0)
; template <int B> __device__ __forceinline__ void pv_reads(VFrag& f, int vb) {
;   constexpr int base = (B >> 2) * 16384 + (B & 3) * 512;
;   f.l0 = tr_read<base + 0 * 4096>(vb); f.h0 = tr_read<base + 0 * 4096 + 2048>(vb); f.l1 = tr_read<base + 1 * 4096>(vb); f.h1 = tr_read<base + 1 * 4096 + 2048>(vb);
;   f.l2 = tr_read<base + 2 * 4096>(vb); f.h2 = tr_read<base + 2 * 4096 + 2048>(vb); f.l3 = tr_read<base + 3 * 4096>(vb); f.h3 = tr_read<base + 3 * 4096 + 2048>(vb);
; }
; __device__ __forceinline__ void pv_mma(f32x16& od, const VFrag& f, bf16x8 pa0, bf16x8 pa1, bf16x8 pa2, bf16x8 pa3) {
;     ...
;   od = __builtin_amdgcn_mfma_f32_32x32x16_bf16(pa0, PKV(f.l0, f.h0), od, 0, 0, 0);
;   od = __builtin_amdgcn_mfma_f32_32x32x16_bf16(pa1, PKV(f.l1, f.h1), od, 0, 0, 0);
;   od = __builtin_amdgcn_mfma_f32_32x32x16_bf16(pa2, PKV(f.l2, f.h2), od, 0, 0, 0);
;   od = __builtin_amdgcn_mfma_f32_32x32x16_bf16(pa3, PKV(f.l3, f.h3), od, 0, 0, 0);
;     ...
; }
; __device__ __forceinline__ void pv_all(f32x16* o, int vb, bf16x8 pa0, bf16x8 pa1, bf16x8 pa2, bf16x8 pa3) {
;   VFrag fc, fn;
;   pv_reads<0>(fc, vb);
;   PV_STEP(0); PV_STEP(1); PV_STEP(2); PV_STEP(3); PV_STEP(4); PV_STEP(5); PV_STEP(6);
;   asm volatile("s_waitcnt lgkmcnt(0)" ::: "memory"); SBAR(); pv_mma(o[7], fc, pa0, pa1, pa2, pa3);
; }
	v_mfma_f32_16x16x32_bf16 v[82:85], v[146:149], v[130:133], v[82:85]
	v_mfma_f32_16x16x32_bf16 v[86:89], v[146:149], v[134:137], v[86:89]
	v_mfma_f32_16x16x32_bf16 v[82:85], v[150:153], v[138:141], v[82:85]
	v_mfma_f32_16x16x32_bf16 v[86:89], v[150:153], v[142:145], v[86:89]
	ds_read_b64_tr_b16 v[146:147], v244 offset:16640
	ds_read_b64_tr_b16 v[148:149], v244 offset:20736
	ds_read_b64_tr_b16 v[150:151], v244 offset:24832
	ds_read_b64_tr_b16 v[152:153], v244 offset:28928
	s_waitcnt lgkmcnt(8)
	v_mfma_f32_16x16x32_bf16 v[90:93], v[154:157], v[130:133], v[90:93]
	v_mfma_f32_16x16x32_bf16 v[94:97], v[154:157], v[134:137], v[94:97]
	v_mfma_f32_16x16x32_bf16 v[90:93], v[158:161], v[138:141], v[90:93]
	v_mfma_f32_16x16x32_bf16 v[94:97], v[158:161], v[142:145], v[94:97]
	ds_read_b64_tr_b16 v[154:155], v244 offset:16896
	ds_read_b64_tr_b16 v[156:157], v244 offset:20992
	ds_read_b64_tr_b16 v[158:159], v244 offset:25088
	ds_read_b64_tr_b16 v[160:161], v244 offset:29184
	s_waitcnt lgkmcnt(8)
	v_mfma_f32_16x16x32_bf16 v[66:69], v[194:197], v[130:133], v[66:69]
	v_mfma_f32_16x16x32_bf16 v[70:73], v[194:197], v[134:137], v[70:73]
	v_mfma_f32_16x16x32_bf16 v[66:69], v[198:201], v[138:141], v[66:69]
	v_mfma_f32_16x16x32_bf16 v[70:73], v[198:201], v[142:145], v[70:73]
	ds_read_b64_tr_b16 v[194:195], v244 offset:17152
	ds_read_b64_tr_b16 v[196:197], v244 offset:21248
	ds_read_b64_tr_b16 v[198:199], v244 offset:25344
	ds_read_b64_tr_b16 v[200:201], v244 offset:29440
	s_waitcnt lgkmcnt(8)
	v_mfma_f32_16x16x32_bf16 v[74:77], v[146:149], v[130:133], v[74:77]
	v_mfma_f32_16x16x32_bf16 v[78:81], v[146:149], v[134:137], v[78:81]
	v_mfma_f32_16x16x32_bf16 v[74:77], v[150:153], v[138:141], v[74:77]
	v_mfma_f32_16x16x32_bf16 v[78:81], v[150:153], v[142:145], v[78:81]
	ds_read_b64_tr_b16 v[146:147], v244 offset:17408
	ds_read_b64_tr_b16 v[148:149], v244 offset:21504
	ds_read_b64_tr_b16 v[150:151], v244 offset:25600
	ds_read_b64_tr_b16 v[152:153], v244 offset:29696
	s_waitcnt lgkmcnt(8)
	v_mfma_f32_16x16x32_bf16 v[50:53], v[154:157], v[130:133], v[50:53]
	v_mfma_f32_16x16x32_bf16 v[54:57], v[154:157], v[134:137], v[54:57]
	v_mfma_f32_16x16x32_bf16 v[50:53], v[158:161], v[138:141], v[50:53]
	v_mfma_f32_16x16x32_bf16 v[54:57], v[158:161], v[142:145], v[54:57]
	ds_read_b64_tr_b16 v[154:155], v244 offset:17664
	ds_read_b64_tr_b16 v[156:157], v244 offset:21760
	ds_read_b64_tr_b16 v[158:159], v244 offset:25856
	ds_read_b64_tr_b16 v[160:161], v244 offset:29952
	s_waitcnt lgkmcnt(8)
	v_mfma_f32_16x16x32_bf16 v[58:61], v[194:197], v[130:133], v[58:61]
	v_mfma_f32_16x16x32_bf16 v[62:65], v[194:197], v[134:137], v[62:65]
	v_mfma_f32_16x16x32_bf16 v[58:61], v[198:201], v[138:141], v[58:61]
	v_mfma_f32_16x16x32_bf16 v[62:65], v[198:201], v[142:145], v[62:65]
	ds_read_b64_tr_b16 v[194:195], v244 offset:17920
	ds_read_b64_tr_b16 v[196:197], v244 offset:22016
	ds_read_b64_tr_b16 v[198:199], v244 offset:26112
	ds_read_b64_tr_b16 v[200:201], v244 offset:30208
	s_waitcnt lgkmcnt(8)
	v_mfma_f32_16x16x32_bf16 v[34:37], v[146:149], v[130:133], v[34:37]
	v_mfma_f32_16x16x32_bf16 v[38:41], v[146:149], v[134:137], v[38:41]
	v_mfma_f32_16x16x32_bf16 v[34:37], v[150:153], v[138:141], v[34:37]
	v_mfma_f32_16x16x32_bf16 v[38:41], v[150:153], v[142:145], v[38:41]
	ds_read_b64_tr_b16 v[146:147], v244 offset:18176
	ds_read_b64_tr_b16 v[148:149], v244 offset:22272
	ds_read_b64_tr_b16 v[150:151], v244 offset:26368
	ds_read_b64_tr_b16 v[152:153], v244 offset:30464
	s_waitcnt lgkmcnt(8)
	v_mfma_f32_16x16x32_bf16 v[42:45], v[154:157], v[130:133], v[42:45]
	v_mfma_f32_16x16x32_bf16 v[46:49], v[154:157], v[134:137], v[46:49]
	v_mfma_f32_16x16x32_bf16 v[42:45], v[158:161], v[138:141], v[42:45]
	v_mfma_f32_16x16x32_bf16 v[46:49], v[158:161], v[142:145], v[46:49]
	s_waitcnt lgkmcnt(4)
	v_mfma_f32_16x16x32_bf16 v[18:21], v[194:197], v[130:133], v[18:21]
	v_mfma_f32_16x16x32_bf16 v[22:25], v[194:197], v[134:137], v[22:25]
	v_mfma_f32_16x16x32_bf16 v[18:21], v[198:201], v[138:141], v[18:21]
	v_mfma_f32_16x16x32_bf16 v[22:25], v[198:201], v[142:145], v[22:25]
	s_waitcnt lgkmcnt(0)
	v_mfma_f32_16x16x32_bf16 v[26:29], v[146:149], v[130:133], v[26:29]
	v_mfma_f32_16x16x32_bf16 v[30:33], v[146:149], v[134:137], v[30:33]
	v_mfma_f32_16x16x32_bf16 v[26:29], v[150:153], v[138:141], v[26:29]
	v_mfma_f32_16x16x32_bf16 v[30:33], v[150:153], v[142:145], v[30:33]

; __device__ __forceinline__ void partialSM(f32x16& p0, f32x16& p1, float& m_reg, float& mn, float& alpha) {
;     ...
;   for (int r = 0; r < 16; ++r) p0[r] = fmaf(p0[r], C, mnC); for (int r = 0; r < 16; ++r) p1[r] = fmaf(p1[r], C, mnC);
;   for (int r = 0; r < 16; ++r) p0[r] = __builtin_amdgcn_exp2f(p0[r]);
; }
; __device__ __forceinline__ void finishSM(f32x16& p0, f32x16& p1, float alpha, float& l_reg, bf16x8& pa0, bf16x8& pa1, bf16x8& pa2, bf16x8& pa3) {
;   for (int r = 0; r < 16; ++r) p1[r] = __builtin_amdgcn_exp2f(p1[r]);
;   float ps = 0; for (int r = 0; r < 16; ++r) ps += p0[r]; for (int r = 0; r < 16; ++r) ps += p1[r];
;   { auto rr = __builtin_amdgcn_permlane32_swap(__float_as_uint(ps), __float_as_uint(ps), false, false);
;     ps = __uint_as_float(rr[0]) + __uint_as_float(rr[1]); }
;   l_reg = l_reg * alpha + ps;
;     ...
;   PK4(p0, 0, pa0); PK4(p0, 8, pa1); PK4(p1, 0, pa2); PK4(p1, 8, pa3);
;     ...
; }
; __device__ __forceinline__ void attn_body256(const bf16_t* __restrict__ Qb, const bf16_t* __restrict__ Kh, const bf16_t* __restrict__ Vh,
;                                              bf16_t* Ob, int seq, unsigned char* lds, float lam, int MODE, bf16_t* Ab, const float* wsub) {
;     ...
;     asm volatile("s_waitcnt vmcnt(0)" ::: "memory"); __syncthreads();
;     if (j + 2 < NT) A2_DMA(j + 2, b);
.Lat_y_noresc:
	v_mul_f32_e32 v198, 0xbe0293ee, v249
	v_mul_f32_e32 v199, 0xbe0293ee, v246
	v_fmamk_f32 v130, v130, 0x3e0293ee, v198
	v_fmamk_f32 v131, v131, 0x3e0293ee, v198
	v_fmamk_f32 v132, v132, 0x3e0293ee, v198
	v_fmamk_f32 v133, v133, 0x3e0293ee, v198
	v_fmamk_f32 v134, v134, 0x3e0293ee, v199
	v_fmamk_f32 v135, v135, 0x3e0293ee, v199
	v_fmamk_f32 v136, v136, 0x3e0293ee, v199
	v_fmamk_f32 v137, v137, 0x3e0293ee, v199
	v_fmamk_f32 v138, v138, 0x3e0293ee, v198
	v_fmamk_f32 v139, v139, 0x3e0293ee, v198
	v_fmamk_f32 v140, v140, 0x3e0293ee, v198
	v_fmamk_f32 v141, v141, 0x3e0293ee, v198
	v_fmamk_f32 v142, v142, 0x3e0293ee, v199
	v_fmamk_f32 v143, v143, 0x3e0293ee, v199
	v_fmamk_f32 v144, v144, 0x3e0293ee, v199
	v_fmamk_f32 v145, v145, 0x3e0293ee, v199
	v_fmamk_f32 v146, v146, 0x3e0293ee, v198
	v_fmamk_f32 v147, v147, 0x3e0293ee, v198
	v_fmamk_f32 v148, v148, 0x3e0293ee, v198
	v_fmamk_f32 v149, v149, 0x3e0293ee, v198
	v_fmamk_f32 v150, v150, 0x3e0293ee, v199
	v_fmamk_f32 v151, v151, 0x3e0293ee, v199
	v_fmamk_f32 v152, v152, 0x3e0293ee, v199
	v_fmamk_f32 v153, v153, 0x3e0293ee, v199
	v_fmamk_f32 v154, v154, 0x3e0293ee, v198
	v_fmamk_f32 v155, v155, 0x3e0293ee, v198
	v_fmamk_f32 v156, v156, 0x3e0293ee, v198
	v_fmamk_f32 v157, v157, 0x3e0293ee, v198
	v_fmamk_f32 v158, v158, 0x3e0293ee, v199
	v_fmamk_f32 v159, v159, 0x3e0293ee, v199
	v_fmamk_f32 v160, v160, 0x3e0293ee, v199
	v_fmamk_f32 v161, v161, 0x3e0293ee, v199
	v_exp_f32_e32 v130, v130
	v_exp_f32_e32 v131, v131
	v_exp_f32_e32 v132, v132
	v_exp_f32_e32 v133, v133
	v_exp_f32_e32 v134, v134
	v_exp_f32_e32 v135, v135
	v_exp_f32_e32 v136, v136
	v_exp_f32_e32 v137, v137
	v_exp_f32_e32 v138, v138
	v_exp_f32_e32 v139, v139
	v_exp_f32_e32 v140, v140
	v_exp_f32_e32 v141, v141
	v_exp_f32_e32 v142, v142
	v_exp_f32_e32 v143, v143
	v_exp_f32_e32 v144, v144
	v_exp_f32_e32 v145, v145
	v_exp_f32_e32 v146, v146
	v_exp_f32_e32 v147, v147
	v_exp_f32_e32 v148, v148
	v_exp_f32_e32 v149, v149
	v_exp_f32_e32 v150, v150
	v_exp_f32_e32 v151, v151
	v_exp_f32_e32 v152, v152
	v_exp_f32_e32 v153, v153
	v_exp_f32_e32 v154, v154
	v_exp_f32_e32 v155, v155
	v_exp_f32_e32 v156, v156
	v_exp_f32_e32 v157, v157
	v_exp_f32_e32 v158, v158
	v_exp_f32_e32 v159, v159
	v_exp_f32_e32 v160, v160
	v_exp_f32_e32 v161, v161
	v_add_f32_e32 v194, v130, v131
	v_add_f32_e32 v194, v194, v132
	v_add_f32_e32 v194, v194, v133
	v_add_f32_e32 v194, v194, v138
	v_add_f32_e32 v194, v194, v139
	v_add_f32_e32 v194, v194, v140
	v_add_f32_e32 v194, v194, v141
	v_add_f32_e32 v194, v194, v146
	v_add_f32_e32 v194, v194, v147
	v_add_f32_e32 v194, v194, v148
	v_add_f32_e32 v194, v194, v149
	v_add_f32_e32 v194, v194, v154
	v_add_f32_e32 v194, v194, v155
	v_add_f32_e32 v194, v194, v156
	v_add_f32_e32 v194, v194, v157
	v_add_f32_e32 v195, v134, v135
	v_add_f32_e32 v195, v195, v136
	v_add_f32_e32 v195, v195, v137
	v_add_f32_e32 v195, v195, v142
	v_add_f32_e32 v195, v195, v143
	v_add_f32_e32 v195, v195, v144
	v_add_f32_e32 v195, v195, v145
	v_add_f32_e32 v195, v195, v150
	v_add_f32_e32 v195, v195, v151
	v_add_f32_e32 v195, v195, v152
	v_add_f32_e32 v195, v195, v153
	v_add_f32_e32 v195, v195, v158
	v_add_f32_e32 v195, v195, v159
	v_add_f32_e32 v195, v195, v160
	v_add_f32_e32 v195, v195, v161
	v_fma_f32 v250, v250, v236, v194
	v_fma_f32 v234, v234, v240, v195
	v_cvt_pk_bf16_f32 v130, v130, v131
	v_cvt_pk_bf16_f32 v131, v132, v133
	v_cvt_pk_bf16_f32 v132, v138, v139
	v_cvt_pk_bf16_f32 v133, v140, v141
	v_cvt_pk_bf16_f32 v134, v134, v135
	v_cvt_pk_bf16_f32 v135, v136, v137
	v_cvt_pk_bf16_f32 v136, v142, v143
	v_cvt_pk_bf16_f32 v137, v144, v145
	v_cvt_pk_bf16_f32 v138, v146, v147
	v_cvt_pk_bf16_f32 v139, v148, v149
	v_cvt_pk_bf16_f32 v140, v154, v155
	v_cvt_pk_bf16_f32 v141, v156, v157
	v_cvt_pk_bf16_f32 v142, v150, v151
	v_cvt_pk_bf16_f32 v143, v152, v153
	v_cvt_pk_bf16_f32 v144, v158, v159
	v_cvt_pk_bf16_f32 v145, v160, v161
	s_waitcnt vmcnt(0)
	s_barrier
	s_cmp_ge_u32 s13, s19
	s_cbranch_scc1 .Lat_y_nodma
	s_add_i32 s9, s22, s24
	v_lshl_add_u64 v[194:195], v[220:221], 0, s[14:15]
	s_mov_b32 m0, s9
	s_add_i32 s8, s21, s100
	global_load_lds_dwordx4 v[194:195], off
	v_lshl_add_u64 v[194:195], v[224:225], 0, s[14:15]
	s_add_i32 s16, s8, 0x4000
	v_lshl_add_u64 v[196:197], v[194:195], 0, s[54:55]
	s_mov_b32 m0, s8
	v_lshl_add_u64 v[194:195], v[194:195], 0, s[4:5]
	global_load_lds_dwordx4 v[196:197], off
	s_mov_b32 m0, s16
	s_nop 0
	global_load_lds_dwordx4 v[194:195], off
	v_lshl_add_u64 v[194:195], v[222:223], 0, s[14:15]
	s_add_i32 m0, s9, 0x2000
	s_nop 0
	global_load_lds_dwordx4 v[194:195], off
	v_lshl_add_u64 v[194:195], v[226:227], 0, s[14:15]
	v_lshl_add_u64 v[196:197], v[194:195], 0, s[54:55]
	s_add_i32 m0, s8, 0x2000
	v_lshl_add_u64 v[194:195], v[194:195], 0, s[4:5]
	global_load_lds_dwordx4 v[196:197], off
	s_add_i32 m0, s8, 0x6000
	s_nop 0
	global_load_lds_dwordx4 v[194:195], off
; #define SBAR() __builtin_amdgcn_sched_barrier(0)
; __device__ __forceinline__ int crow(int r, int hi) { return (r & 3) + 8 * (r >> 2) + 4 * hi; }
; __device__ __forceinline__ int crow(int r, int hi) { return (r & 3) + 8 * (r >> 2) + 4 * hi; }
; template <int B> __device__ __forceinline__ void pv_reads(VFrag& f, int vb) {
;   constexpr int base = (B >> 2) * 16384 + (B & 3) * 512;
;   f.l0 = tr_read<base + 0 * 4096>(vb); f.h0 = tr_read<base + 0 * 4096 + 2048>(vb); f.l1 = tr_read<base + 1 * 4096>(vb); f.h1 = tr_read<base + 1 * 4096 + 2048>(vb);
;   f.l2 = tr_read<base + 2 * 4096>(vb); f.h2 = tr_read<base + 2 * 4096 + 2048>(vb); f.l3 = tr_read<base + 3 * 4096>(vb); f.h3 = tr_read<base + 3 * 4096 + 2048>(vb);
; }
; __device__ __forceinline__ void pv_mma(f32x16& od, const VFrag& f, bf16x8 pa0, bf16x8 pa1, bf16x8 pa2, bf16x8 pa3) {
;     ...
;   od = __builtin_amdgcn_mfma_f32_32x32x16_bf16(pa0, PKV(f.l0, f.h0), od, 0, 0, 0);
;   od = __builtin_amdgcn_mfma_f32_32x32x16_bf16(pa1, PKV(f.l1, f.h1), od, 0, 0, 0);
;   od = __builtin_amdgcn_mfma_f32_32x32x16_bf16(pa2, PKV(f.l2, f.h2), od, 0, 0, 0);
;   od = __builtin_amdgcn_mfma_f32_32x32x16_bf16(pa3, PKV(f.l3, f.h3), od, 0, 0, 0);
;     ...
; }
; __device__ __forceinline__ void attn_body256(const bf16_t* __restrict__ Qb, const bf16_t* __restrict__ Kh, const bf16_t* __restrict__ Vh,
;                                              bf16_t* Ob, int seq, unsigned char* lds, float lam, int MODE, bf16_t* Ab, const float* wsub) {
;     ...
;   for (int j = 0; j < NT; ++j) {
;     const int b = j & 1;
;     f32x16 p0, p1; float mn, alpha; bf16x8 pa0, pa1, pa2, pa3;
;     SBAR(); qkt(p0, p1, (const bf16_t*)(lds + A2_KOFF + b * A2_KBUF), qr, r32, hi);
;     partialSM(p0, p1, m_reg, mn, alpha);
;     if (__any(alpha < 1.f)) { if (hi == 0) al_l[r32] = alpha; asm volatile("s_waitcnt lgkmcnt(0)" ::: "memory");
; #pragma unroll
;       for (int r = 0; r < 16; ++r) { const float a = al_l[crow(r, hi)];
; #pragma unroll
;         for (int d = 0; d < 8; ++d) o[d][r] *= a; } }
;     finishSM(p0, p1, alpha, l_reg, pa0, pa1, pa2, pa3); SBAR();
;     pv_all(o, vb0 + b * A2_VBUF, pa0, pa1, pa2, pa3);
;     asm volatile("s_waitcnt vmcnt(0)" ::: "memory"); __syncthreads();
;     if (j + 2 < NT) A2_DMA(j + 2, b);
;   }
.Lat_y_nodma:
	s_mov_b32 s101, s98
	s_mov_b32 s98, s99
	s_mov_b32 s99, s100
	s_mov_b32 s100, s101
	s_add_u32 s14, s14, 0x40000
	s_addc_u32 s15, s15, 0
	s_add_i32 s13, s13, 1
	s_cmp_eq_u32 s23, s14
	s_cbranch_scc0 .Lat_y_top
	v_add_u32_e32 v244, s100, v248
	ds_read_b64_tr_b16 v[146:147], v244
	ds_read_b64_tr_b16 v[148:149], v244 offset:4096
	ds_read_b64_tr_b16 v[150:151], v244 offset:8192
	ds_read_b64_tr_b16 v[152:153], v244 offset:12288
	ds_read_b64_tr_b16 v[154:155], v244 offset:256
	ds_read_b64_tr_b16 v[156:157], v244 offset:4352
	ds_read_b64_tr_b16 v[158:159], v244 offset:8448
	ds_read_b64_tr_b16 v[160:161], v244 offset:12544
	ds_read_b64_tr_b16 v[194:195], v244 offset:512
	ds_read_b64_tr_b16 v[196:197], v244 offset:4608
	ds_read_b64_tr_b16 v[198:199], v244 offset:8704
	ds_read_b64_tr_b16 v[200:201], v244 offset:12800
	s_waitcnt lgkmcnt(8)
	v_mfma_f32_16x16x32_bf16 v[2:5], v[146:149], v[130:133], v[2:5]
	v_mfma_f32_16x16x32_bf16 v[6:9], v[146:149], v[134:137], v[6:9]
	v_mfma_f32_16x16x32_bf16 v[2:5], v[150:153], v[138:141], v[2:5]
	v_mfma_f32_16x16x32_bf16 v[6:9], v[150:153], v[142:145], v[6:9]
	ds_read_b64_tr_b16 v[146:147], v244 offset:768
	ds_read_b64_tr_b16 v[148:149], v244 offset:4864
	ds_read_b64_tr_b16 v[150:151], v244 offset:8960
	ds_read_b64_tr_b16 v[152:153], v244 offset:13056
	s_waitcnt lgkmcnt(8)
	v_mfma_f32_16x16x32_bf16 v[10:13], v[154:157], v[130:133], v[10:13]
	v_mfma_f32_16x16x32_bf16 v[14:17], v[154:157], v[134:137], v[14:17]
	v_mfma_f32_16x16x32_bf16 v[10:13], v[158:161], v[138:141], v[10:13]
	v_mfma_f32_16x16x32_bf16 v[14:17], v[158:161], v[142:145], v[14:17]
	ds_read_b64_tr_b16 v[154:155], v244 offset:1024
	ds_read_b64_tr_b16 v[156:157], v244 offset:5120
	ds_read_b64_tr_b16 v[158:159], v244 offset:9216
	ds_read_b64_tr_b16 v[160:161], v244 offset:13312
	s_waitcnt lgkmcnt(8)
	v_mfma_f32_16x16x32_bf16 v[114:117], v[194:197], v[130:133], v[114:117]
	v_mfma_f32_16x16x32_bf16 v[118:121], v[194:197], v[134:137], v[118:121]
	v_mfma_f32_16x16x32_bf16 v[114:117], v[198:201], v[138:141], v[114:117]
	v_mfma_f32_16x16x32_bf16 v[118:121], v[198:201], v[142:145], v[118:121]
	ds_read_b64_tr_b16 v[194:195], v244 offset:1280
	ds_read_b64_tr_b16 v[196:197], v244 offset:5376
	ds_read_b64_tr_b16 v[198:199], v244 offset:9472
	ds_read_b64_tr_b16 v[200:201], v244 offset:13568
	s_waitcnt lgkmcnt(8)
	v_mfma_f32_16x16x32_bf16 v[122:125], v[146:149], v[130:133], v[122:125]
	v_mfma_f32_16x16x32_bf16 v[126:129], v[146:149], v[134:137], v[126:129]
	v_mfma_f32_16x16x32_bf16 v[122:125], v[150:153], v[138:141], v[122:125]
	v_mfma_f32_16x16x32_bf16 v[126:129], v[150:153], v[142:145], v[126:129]
	ds_read_b64_tr_b16 v[146:147], v244 offset:1536
	ds_read_b64_tr_b16 v[148:149], v244 offset:5632
	ds_read_b64_tr_b16 v[150:151], v244 offset:9728
	ds_read_b64_tr_b16 v[152:153], v244 offset:13824
	s_waitcnt lgkmcnt(8)
	v_mfma_f32_16x16x32_bf16 v[98:101], v[154:157], v[130:133], v[98:101]
	v_mfma_f32_16x16x32_bf16 v[102:105], v[154:157], v[134:137], v[102:105]
	v_mfma_f32_16x16x32_bf16 v[98:101], v[158:161], v[138:141], v[98:101]
	v_mfma_f32_16x16x32_bf16 v[102:105], v[158:161], v[142:145], v[102:105]
	ds_read_b64_tr_b16 v[154:155], v244 offset:1792
	ds_read_b64_tr_b16 v[156:157], v244 offset:5888
	ds_read_b64_tr_b16 v[158:159], v244 offset:9984
	ds_read_b64_tr_b16 v[160:161], v244 offset:14080
	s_waitcnt lgkmcnt(8)
	v_mfma_f32_16x16x32_bf16 v[106:109], v[194:197], v[130:133], v[106:109]
	v_mfma_f32_16x16x32_bf16 v[110:113], v[194:197], v[134:137], v[110:113]
	v_mfma_f32_16x16x32_bf16 v[106:109], v[198:201], v[138:141], v[106:109]
	v_mfma_f32_16x16x32_bf16 v[110:113], v[198:201], v[142:145], v[110:113]
	ds_read_b64_tr_b16 v[194:195], v244 offset:16384
	ds_read_b64_tr_b16 v[196:197], v244 offset:20480
	ds_read_b64_tr_b16 v[198:199], v244 offset:24576
	ds_read_b64_tr_b16 v[200:201], v244 offset:28672
	s_waitcnt lgkmcnt(8)
	v_mfma_f32_16x16x32_bf16 v[82:85], v[146:149], v[130:133], v[82:85]
	v_mfma_f32_16x16x32_bf16 v[86:89], v[146:149], v[134:137], v[86:89]
	v_mfma_f32_16x16x32_bf16 v[82:85], v[150:153], v[138:141], v[82:85]
	v_mfma_f32_16x16x32_bf16 v[86:89], v[150:153], v[142:145], v[86:89]
	ds_read_b64_tr_b16 v[146:147], v244 offset:16640
	ds_read_b64_tr_b16 v[148:149], v244 offset:20736
	ds_read_b64_tr_b16 v[150:151], v244 offset:24832
	ds_read_b64_tr_b16 v[152:153], v244 offset:28928
	s_waitcnt lgkmcnt(8)
	v_mfma_f32_16x16x32_bf16 v[90:93], v[154:157], v[130:133], v[90:93]
	v_mfma_f32_16x16x32_bf16 v[94:97], v[154:157], v[134:137], v[94:97]
	v_mfma_f32_16x16x32_bf16 v[90:93], v[158:161], v[138:141], v[90:93]
	v_mfma_f32_16x16x32_bf16 v[94:97], v[158:161], v[142:145], v[94:97]
	ds_read_b64_tr_b16 v[154:155], v244 offset:16896
	ds_read_b64_tr_b16 v[156:157], v244 offset:20992
	ds_read_b64_tr_b16 v[158:159], v244 offset:25088
	ds_read_b64_tr_b16 v[160:161], v244 offset:29184
	s_waitcnt lgkmcnt(8)
	v_mfma_f32_16x16x32_bf16 v[66:69], v[194:197], v[130:133], v[66:69]
	v_mfma_f32_16x16x32_bf16 v[70:73], v[194:197], v[134:137], v[70:73]
	v_mfma_f32_16x16x32_bf16 v[66:69], v[198:201], v[138:141], v[66:69]
	v_mfma_f32_16x16x32_bf16 v[70:73], v[198:201], v[142:145], v[70:73]
	ds_read_b64_tr_b16 v[194:195], v244 offset:17152
	ds_read_b64_tr_b16 v[196:197], v244 offset:21248
	ds_read_b64_tr_b16 v[198:199], v244 offset:25344
	ds_read_b64_tr_b16 v[200:201], v244 offset:29440
	s_waitcnt lgkmcnt(8)
	v_mfma_f32_16x16x32_bf16 v[74:77], v[146:149], v[130:133], v[74:77]
	v_mfma_f32_16x16x32_bf16 v[78:81], v[146:149], v[134:137], v[78:81]
	v_mfma_f32_16x16x32_bf16 v[74:77], v[150:153], v[138:141], v[74:77]
	v_mfma_f32_16x16x32_bf16 v[78:81], v[150:153], v[142:145], v[78:81]
	ds_read_b64_tr_b16 v[146:147], v244 offset:17408
	ds_read_b64_tr_b16 v[148:149], v244 offset:21504
	ds_read_b64_tr_b16 v[150:151], v244 offset:25600
	ds_read_b64_tr_b16 v[152:153], v244 offset:29696
	s_waitcnt lgkmcnt(8)
; __device__ __forceinline__ bf16_t f2bf(float x) { return (bf16_t)(cvt_pk_bf16(x, x) & 0xffffu); }
; __device__ __forceinline__ float bf2f(bf16_t b) { return __uint_as_float(((unsigned)b) << 16); }
; #define SBAR() __builtin_amdgcn_sched_barrier(0)
; __device__ __forceinline__ int crow(int r, int hi) { return (r & 3) + 8 * (r >> 2) + 4 * hi; }
; __device__ __forceinline__ void pv_mma(f32x16& od, const VFrag& f, bf16x8 pa0, bf16x8 pa1, bf16x8 pa2, bf16x8 pa3) {
;     ...
;   od = __builtin_amdgcn_mfma_f32_32x32x16_bf16(pa0, PKV(f.l0, f.h0), od, 0, 0, 0);
;   od = __builtin_amdgcn_mfma_f32_32x32x16_bf16(pa1, PKV(f.l1, f.h1), od, 0, 0, 0);
;   od = __builtin_amdgcn_mfma_f32_32x32x16_bf16(pa2, PKV(f.l2, f.h2), od, 0, 0, 0);
;   od = __builtin_amdgcn_mfma_f32_32x32x16_bf16(pa3, PKV(f.l3, f.h3), od, 0, 0, 0);
;     ...
; }
; __device__ __forceinline__ void pv_all(f32x16* o, int vb, bf16x8 pa0, bf16x8 pa1, bf16x8 pa2, bf16x8 pa3) {
;   VFrag fc, fn;
;   pv_reads<0>(fc, vb);
;   PV_STEP(0); PV_STEP(1); PV_STEP(2); PV_STEP(3); PV_STEP(4); PV_STEP(5); PV_STEP(6);
;   asm volatile("s_waitcnt lgkmcnt(0)" ::: "memory"); SBAR(); pv_mma(o[7], fc, pa0, pa1, pa2, pa3);
; }
; __device__ __forceinline__ void attn_body256(const bf16_t* __restrict__ Qb, const bf16_t* __restrict__ Kh, const bf16_t* __restrict__ Vh,
;                                              bf16_t* Ob, int seq, unsigned char* lds, float lam, int MODE, bf16_t* Ab, const float* wsub) {
;     ...
;   if (hi == 0) li_l[r32] = l_reg; asm volatile("s_waitcnt lgkmcnt(0)" ::: "memory");
;   float rli[16];
; #pragma unroll
;   for (int r = 0; r < 16; ++r) rli[r] = __builtin_amdgcn_rcpf(li_l[crow(r, hi)]);
;   bf16_t* Ow = Ob + (long)(wid * QBLK) * LDO;
;   if (MODE == 0) {
; #pragma unroll
;     for (int r = 0; r < 16; ++r) { const int orow = crow(r, hi);
; #pragma unroll
;       for (int d0 = 0; d0 < 8; ++d0) Ow[(long)orow * LDO + d0 * 32 + r32] = f2bf(o[d0][r] * rli[r]); }
;   } else {
;     bf16_t* Aw = Ab + (long)(wid * QBLK) * LDO;
;     float wv[8];
; #pragma unroll
;     for (int d0 = 0; d0 < 8; ++d0) wv[d0] = wsub[d0 * 32 + r32] * (1.f - LAMBDA_INIT);
; #pragma unroll
;     for (int r = 0; r < 16; ++r) { const int orow = crow(r, hi); float ss = 0.f;
; #pragma unroll
;       for (int d0 = 0; d0 < 8; ++d0) { const float v = bf2f(Ow[(long)orow * LDO + d0 * 32 + r32]) - lam * (o[d0][r] * rli[r]); o[d0][r] = v; ss += v * v; }
	v_mfma_f32_16x16x32_bf16 v[50:53], v[154:157], v[130:133], v[50:53]
	v_mfma_f32_16x16x32_bf16 v[54:57], v[154:157], v[134:137], v[54:57]
	v_mfma_f32_16x16x32_bf16 v[50:53], v[158:161], v[138:141], v[50:53]
	v_mfma_f32_16x16x32_bf16 v[54:57], v[158:161], v[142:145], v[54:57]
	ds_read_b64_tr_b16 v[154:155], v244 offset:17664
	ds_read_b64_tr_b16 v[156:157], v244 offset:21760
	ds_read_b64_tr_b16 v[158:159], v244 offset:25856
	ds_read_b64_tr_b16 v[160:161], v244 offset:29952
	s_waitcnt lgkmcnt(8)
	v_mfma_f32_16x16x32_bf16 v[58:61], v[194:197], v[130:133], v[58:61]
	v_mfma_f32_16x16x32_bf16 v[62:65], v[194:197], v[134:137], v[62:65]
	v_mfma_f32_16x16x32_bf16 v[58:61], v[198:201], v[138:141], v[58:61]
	v_mfma_f32_16x16x32_bf16 v[62:65], v[198:201], v[142:145], v[62:65]
	ds_read_b64_tr_b16 v[194:195], v244 offset:17920
	ds_read_b64_tr_b16 v[196:197], v244 offset:22016
	ds_read_b64_tr_b16 v[198:199], v244 offset:26112
	ds_read_b64_tr_b16 v[200:201], v244 offset:30208
	s_waitcnt lgkmcnt(8)
	v_mfma_f32_16x16x32_bf16 v[34:37], v[146:149], v[130:133], v[34:37]
	v_mfma_f32_16x16x32_bf16 v[38:41], v[146:149], v[134:137], v[38:41]
	v_mfma_f32_16x16x32_bf16 v[34:37], v[150:153], v[138:141], v[34:37]
	v_mfma_f32_16x16x32_bf16 v[38:41], v[150:153], v[142:145], v[38:41]
	ds_read_b64_tr_b16 v[146:147], v244 offset:18176
	ds_read_b64_tr_b16 v[148:149], v244 offset:22272
	ds_read_b64_tr_b16 v[150:151], v244 offset:26368
	ds_read_b64_tr_b16 v[152:153], v244 offset:30464
	s_waitcnt lgkmcnt(8)
	v_mfma_f32_16x16x32_bf16 v[42:45], v[154:157], v[130:133], v[42:45]
	v_mfma_f32_16x16x32_bf16 v[46:49], v[154:157], v[134:137], v[46:49]
	v_mfma_f32_16x16x32_bf16 v[42:45], v[158:161], v[138:141], v[42:45]
	v_mfma_f32_16x16x32_bf16 v[46:49], v[158:161], v[142:145], v[46:49]
	s_waitcnt lgkmcnt(4)
	v_mfma_f32_16x16x32_bf16 v[18:21], v[194:197], v[130:133], v[18:21]
	v_mfma_f32_16x16x32_bf16 v[22:25], v[194:197], v[134:137], v[22:25]
	v_mfma_f32_16x16x32_bf16 v[18:21], v[198:201], v[138:141], v[18:21]
	v_mfma_f32_16x16x32_bf16 v[22:25], v[198:201], v[142:145], v[22:25]
	s_waitcnt lgkmcnt(0)
	v_mfma_f32_16x16x32_bf16 v[26:29], v[146:149], v[130:133], v[26:29]
	v_mfma_f32_16x16x32_bf16 v[30:33], v[146:149], v[134:137], v[30:33]
	v_mfma_f32_16x16x32_bf16 v[26:29], v[150:153], v[138:141], v[26:29]
	v_mfma_f32_16x16x32_bf16 v[30:33], v[150:153], v[142:145], v[30:33]
.Lat_epi:
	v_mov_b32_e32 v196, v250
	v_mov_b32_e32 v197, v234
	s_nop 1
	v_permlane32_swap_b32_e32 v250, v196
	v_permlane32_swap_b32_e32 v234, v197
	v_add_f32_e32 v250, v250, v196
	v_add_f32_e32 v234, v234, v197
	v_mov_b32_e32 v196, v250
	v_mov_b32_e32 v197, v234
	s_nop 1
	v_permlane16_swap_b32_e32 v250, v196
	v_permlane16_swap_b32_e32 v234, v197
	v_add_f32_e32 v250, v250, v196
	v_add_f32_e32 v234, v234, v197
	v_rcp_f32_e32 v198, v250
	v_rcp_f32_e32 v199, v234
	v_and_b32_e32 v202, 15, v231
	v_lshlrev_b32_e32 v202, 12, v202
	v_bfe_u32 v203, v231, 4, 2
	v_lshlrev_b32_e32 v210, 4, v203
	v_lshl_add_u32 v202, v203, 3, v202
	v_mov_b32_e32 v203, 0
	v_mov_b32_e32 v208, 0x10000
	v_mov_b32_e32 v209, 0
	s_lshl_b64 s[8:9], s[10:11], 1
	s_add_u32 s6, s92, s8
	s_addc_u32 s7, s93, s9
	s_add_u32 s10, s6, s0
	s_addc_u32 s11, s7, s1
	s_ashr_i32 s13, s12, 31
	s_lshl_b64 s[6:7], s[12:13], 12
	s_add_u32 s6, s10, s6
	s_addc_u32 s7, s11, s7
	s_cmp_lg_u32 s2, 0
	s_mov_b64 s[10:11], -1
	v_lshl_add_u64 v[194:195], s[6:7], 0, v[202:203]
	v_lshl_add_u64 v[196:197], v[194:195], 0, v[208:209]
	s_cmp_lg_u32 s2, 0
	s_cbranch_scc0 .Lat_e682
	s_lshl_b64 s[10:11], s[12:13], 11
	s_add_u32 s2, s76, s8
	s_addc_u32 s8, s77, s9
	v_readlane_b32 s72, v252, 22
	v_readlane_b32 s76, v252, 26
	v_readlane_b32 s77, v252, 27
	v_readlane_b32 s78, v252, 28
	v_readlane_b32 s79, v252, 29
	v_readlane_b32 s80, v252, 30
	v_readlane_b32 s81, v252, 31
	v_readlane_b32 s82, v252, 32
	v_readlane_b32 s83, v252, 33
	v_readlane_b32 s84, v252, 34
	v_readlane_b32 s85, v252, 35
	s_mov_b64 s[20:21], s[76:77]
	s_mov_b64 s[28:29], s[84:85]
	s_add_u32 s2, s2, s0
	s_addc_u32 s8, s8, s1
	s_lshl_b64 s[0:1], s[10:11], 1
	s_add_u32 s0, s2, s0
	s_addc_u32 s1, s8, s1
	s_mov_b32 s2, 0x3b800000
	v_readlane_b32 s73, v252, 23
	v_readlane_b32 s74, v252, 24
	v_readlane_b32 s75, v252, 25
	v_readlane_b32 s72, v254, 62
	v_readlane_b32 s74, v254, 53
	s_mov_b64 s[22:23], s[78:79]
	s_mov_b64 s[24:25], s[80:81]
	s_mov_b64 s[26:27], s[82:83]
	v_readlane_b32 s80, v255, 2
	v_readlane_b32 s78, v255, 0
	v_readlane_b32 s84, v254, 60
	v_readlane_b32 s82, v254, 58
	v_readlane_b32 s76, v254, 55
	v_readlane_b32 s86, v252, 36
	v_readlane_b32 s87, v252, 37
	v_readlane_b32 s73, v254, 63
	v_readlane_b32 s75, v254, 54
	v_readlane_b32 s81, v255, 3
	v_readlane_b32 s79, v255, 1
	v_readlane_b32 s85, v254, 61
	v_readlane_b32 s83, v254, 59
	v_readlane_b32 s77, v254, 56
	s_mov_b64 s[10:11], 0
	v_lshl_add_u64 v[204:205], s[0:1], 0, v[202:203]
	v_lshl_add_u64 v[206:207], v[204:205], 0, v[208:209]
	global_load_dwordx2 v[130:131], v[194:195], off
	global_load_dwordx2 v[132:133], v[194:195], off offset:32
	global_load_dwordx2 v[134:135], v[194:195], off offset:64
	global_load_dwordx2 v[136:137], v[194:195], off offset:96
	global_load_dwordx2 v[138:139], v[194:195], off offset:128
	global_load_dwordx2 v[140:141], v[194:195], off offset:160
	global_load_dwordx2 v[142:143], v[194:195], off offset:192
	global_load_dwordx2 v[144:145], v[194:195], off offset:224
	global_load_dwordx2 v[146:147], v[194:195], off offset:256
	global_load_dwordx2 v[148:149], v[194:195], off offset:288
	global_load_dwordx2 v[150:151], v[194:195], off offset:320
	global_load_dwordx2 v[152:153], v[194:195], off offset:352
	global_load_dwordx2 v[154:155], v[194:195], off offset:384
	global_load_dwordx2 v[156:157], v[194:195], off offset:416
	global_load_dwordx2 v[158:159], v[194:195], off offset:448
	global_load_dwordx2 v[160:161], v[194:195], off offset:480
	global_load_dwordx2 v[162:163], v[196:197], off
	global_load_dwordx2 v[164:165], v[196:197], off offset:32
	global_load_dwordx2 v[166:167], v[196:197], off offset:64
	global_load_dwordx2 v[168:169], v[196:197], off offset:96
	global_load_dwordx2 v[170:171], v[196:197], off offset:128
	global_load_dwordx2 v[172:173], v[196:197], off offset:160
	global_load_dwordx2 v[174:175], v[196:197], off offset:192
	global_load_dwordx2 v[176:177], v[196:197], off offset:224
	global_load_dwordx2 v[178:179], v[196:197], off offset:256
	global_load_dwordx2 v[180:181], v[196:197], off offset:288
	global_load_dwordx2 v[182:183], v[196:197], off offset:320
	global_load_dwordx2 v[184:185], v[196:197], off offset:352
	global_load_dwordx2 v[186:187], v[196:197], off offset:384
	global_load_dwordx2 v[188:189], v[196:197], off offset:416
	global_load_dwordx2 v[190:191], v[196:197], off offset:448
	global_load_dwordx2 v[192:193], v[196:197], off offset:480
	v_mov_b32_e32 v200, 0
	v_mov_b32_e32 v201, 0
	s_waitcnt vmcnt(31)
; __device__ __forceinline__ float bf2f(bf16_t b) { return __uint_as_float(((unsigned)b) << 16); }
; __device__ __forceinline__ int crow(int r, int hi) { return (r & 3) + 8 * (r >> 2) + 4 * hi; }
; __device__ __forceinline__ int crow(int r, int hi) { return (r & 3) + 8 * (r >> 2) + 4 * hi; }
; __device__ __forceinline__ void attn_body256(const bf16_t* __restrict__ Qb, const bf16_t* __restrict__ Kh, const bf16_t* __restrict__ Vh,
;                                              bf16_t* Ob, int seq, unsigned char* lds, float lam, int MODE, bf16_t* Ab, const float* wsub) {
;     ...
;     for (int r = 0; r < 16; ++r) { const int orow = crow(r, hi); float ss = 0.f;
; #pragma unroll
;       for (int d0 = 0; d0 < 8; ++d0) { const float v = bf2f(Ow[(long)orow * LDO + d0 * 32 + r32]) - lam * (o[d0][r] * rli[r]); o[d0][r] = v; ss += v * v; }
	v_lshlrev_b32_e32 v211, 16, v130
	v_mul_f32_e32 v2, v2, v198
	v_fma_f32 v2, -v218, v2, v211
	v_fmac_f32_e32 v200, v2, v2
	v_and_b32_e32 v211, 0xffff0000, v130
	v_mul_f32_e32 v3, v3, v198
	v_fma_f32 v3, -v218, v3, v211
	v_fmac_f32_e32 v200, v3, v3
	v_lshlrev_b32_e32 v211, 16, v131
	v_mul_f32_e32 v4, v4, v198
	v_fma_f32 v4, -v218, v4, v211
	v_fmac_f32_e32 v200, v4, v4
	v_and_b32_e32 v211, 0xffff0000, v131
	v_mul_f32_e32 v5, v5, v198
	v_fma_f32 v5, -v218, v5, v211
	v_fmac_f32_e32 v200, v5, v5
	s_waitcnt vmcnt(30)
	v_lshlrev_b32_e32 v211, 16, v132
	v_mul_f32_e32 v10, v10, v198
	v_fma_f32 v10, -v218, v10, v211
	v_fmac_f32_e32 v200, v10, v10
	v_and_b32_e32 v211, 0xffff0000, v132
	v_mul_f32_e32 v11, v11, v198
	v_fma_f32 v11, -v218, v11, v211
	v_fmac_f32_e32 v200, v11, v11
	v_lshlrev_b32_e32 v211, 16, v133
	v_mul_f32_e32 v12, v12, v198
	v_fma_f32 v12, -v218, v12, v211
	v_fmac_f32_e32 v200, v12, v12
	v_and_b32_e32 v211, 0xffff0000, v133
	v_mul_f32_e32 v13, v13, v198
	v_fma_f32 v13, -v218, v13, v211
	v_fmac_f32_e32 v200, v13, v13
	s_waitcnt vmcnt(29)
	v_lshlrev_b32_e32 v211, 16, v134
	v_mul_f32_e32 v114, v114, v198
	v_fma_f32 v114, -v218, v114, v211
	v_fmac_f32_e32 v200, v114, v114
	v_and_b32_e32 v211, 0xffff0000, v134
	v_mul_f32_e32 v115, v115, v198
	v_fma_f32 v115, -v218, v115, v211
	v_fmac_f32_e32 v200, v115, v115
	v_lshlrev_b32_e32 v211, 16, v135
	v_mul_f32_e32 v116, v116, v198
	v_fma_f32 v116, -v218, v116, v211
	v_fmac_f32_e32 v200, v116, v116
	v_and_b32_e32 v211, 0xffff0000, v135
	v_mul_f32_e32 v117, v117, v198
	v_fma_f32 v117, -v218, v117, v211
	v_fmac_f32_e32 v200, v117, v117
	s_waitcnt vmcnt(28)
	v_lshlrev_b32_e32 v211, 16, v136
	v_mul_f32_e32 v122, v122, v198
	v_fma_f32 v122, -v218, v122, v211
	v_fmac_f32_e32 v200, v122, v122
	v_and_b32_e32 v211, 0xffff0000, v136
	v_mul_f32_e32 v123, v123, v198
	v_fma_f32 v123, -v218, v123, v211
	v_fmac_f32_e32 v200, v123, v123
	v_lshlrev_b32_e32 v211, 16, v137
	v_mul_f32_e32 v124, v124, v198
	v_fma_f32 v124, -v218, v124, v211
	v_fmac_f32_e32 v200, v124, v124
	v_and_b32_e32 v211, 0xffff0000, v137
	v_mul_f32_e32 v125, v125, v198
	v_fma_f32 v125, -v218, v125, v211
	v_fmac_f32_e32 v200, v125, v125
	s_waitcnt vmcnt(27)
	v_lshlrev_b32_e32 v211, 16, v138
	v_mul_f32_e32 v98, v98, v198
	v_fma_f32 v98, -v218, v98, v211
	v_fmac_f32_e32 v200, v98, v98
	v_and_b32_e32 v211, 0xffff0000, v138
	v_mul_f32_e32 v99, v99, v198
	v_fma_f32 v99, -v218, v99, v211
	v_fmac_f32_e32 v200, v99, v99
	v_lshlrev_b32_e32 v211, 16, v139
	v_mul_f32_e32 v100, v100, v198
	v_fma_f32 v100, -v218, v100, v211
	v_fmac_f32_e32 v200, v100, v100
	v_and_b32_e32 v211, 0xffff0000, v139
	v_mul_f32_e32 v101, v101, v198
	v_fma_f32 v101, -v218, v101, v211
	v_fmac_f32_e32 v200, v101, v101
	s_waitcnt vmcnt(26)
	v_lshlrev_b32_e32 v211, 16, v140
	v_mul_f32_e32 v106, v106, v198
	v_fma_f32 v106, -v218, v106, v211
	v_fmac_f32_e32 v200, v106, v106
	v_and_b32_e32 v211, 0xffff0000, v140
	v_mul_f32_e32 v107, v107, v198
	v_fma_f32 v107, -v218, v107, v211
	v_fmac_f32_e32 v200, v107, v107
	v_lshlrev_b32_e32 v211, 16, v141
	v_mul_f32_e32 v108, v108, v198
	v_fma_f32 v108, -v218, v108, v211
	v_fmac_f32_e32 v200, v108, v108
	v_and_b32_e32 v211, 0xffff0000, v141
	v_mul_f32_e32 v109, v109, v198
	v_fma_f32 v109, -v218, v109, v211
	v_fmac_f32_e32 v200, v109, v109
	s_waitcnt vmcnt(25)
	v_lshlrev_b32_e32 v211, 16, v142
	v_mul_f32_e32 v82, v82, v198
	v_fma_f32 v82, -v218, v82, v211
	v_fmac_f32_e32 v200, v82, v82
	v_and_b32_e32 v211, 0xffff0000, v142
	v_mul_f32_e32 v83, v83, v198
	v_fma_f32 v83, -v218, v83, v211
	v_fmac_f32_e32 v200, v83, v83
	v_lshlrev_b32_e32 v211, 16, v143
	v_mul_f32_e32 v84, v84, v198
	v_fma_f32 v84, -v218, v84, v211
	v_fmac_f32_e32 v200, v84, v84
	v_and_b32_e32 v211, 0xffff0000, v143
	v_mul_f32_e32 v85, v85, v198
	v_fma_f32 v85, -v218, v85, v211
	v_fmac_f32_e32 v200, v85, v85
	s_waitcnt vmcnt(24)
	v_lshlrev_b32_e32 v211, 16, v144
	v_mul_f32_e32 v90, v90, v198
	v_fma_f32 v90, -v218, v90, v211
	v_fmac_f32_e32 v200, v90, v90
	v_and_b32_e32 v211, 0xffff0000, v144
	v_mul_f32_e32 v91, v91, v198
	v_fma_f32 v91, -v218, v91, v211
	v_fmac_f32_e32 v200, v91, v91
	v_lshlrev_b32_e32 v211, 16, v145
	v_mul_f32_e32 v92, v92, v198
	v_fma_f32 v92, -v218, v92, v211
	v_fmac_f32_e32 v200, v92, v92
	v_and_b32_e32 v211, 0xffff0000, v145
	v_mul_f32_e32 v93, v93, v198
	v_fma_f32 v93, -v218, v93, v211
	v_fmac_f32_e32 v200, v93, v93
	s_waitcnt vmcnt(23)
	v_lshlrev_b32_e32 v211, 16, v146
	v_mul_f32_e32 v66, v66, v198
	v_fma_f32 v66, -v218, v66, v211
	v_fmac_f32_e32 v200, v66, v66
	v_and_b32_e32 v211, 0xffff0000, v146
	v_mul_f32_e32 v67, v67, v198
	v_fma_f32 v67, -v218, v67, v211
	v_fmac_f32_e32 v200, v67, v67
	v_lshlrev_b32_e32 v211, 16, v147
	v_mul_f32_e32 v68, v68, v198
	v_fma_f32 v68, -v218, v68, v211
	v_fmac_f32_e32 v200, v68, v68
	v_and_b32_e32 v211, 0xffff0000, v147
	v_mul_f32_e32 v69, v69, v198
	v_fma_f32 v69, -v218, v69, v211
	v_fmac_f32_e32 v200, v69, v69
	s_waitcnt vmcnt(22)
	v_lshlrev_b32_e32 v211, 16, v148
	v_mul_f32_e32 v74, v74, v198
	v_fma_f32 v74, -v218, v74, v211
	v_fmac_f32_e32 v200, v74, v74
	v_and_b32_e32 v211, 0xffff0000, v148
	v_mul_f32_e32 v75, v75, v198
	v_fma_f32 v75, -v218, v75, v211
	v_fmac_f32_e32 v200, v75, v75
	v_lshlrev_b32_e32 v211, 16, v149
	v_mul_f32_e32 v76, v76, v198
	v_fma_f32 v76, -v218, v76, v211
	v_fmac_f32_e32 v200, v76, v76
	v_and_b32_e32 v211, 0xffff0000, v149
	v_mul_f32_e32 v77, v77, v198
	v_fma_f32 v77, -v218, v77, v211
	v_fmac_f32_e32 v200, v77, v77
	s_waitcnt vmcnt(21)
; __device__ __forceinline__ float bf2f(bf16_t b) { return __uint_as_float(((unsigned)b) << 16); }
; __device__ __forceinline__ int crow(int r, int hi) { return (r & 3) + 8 * (r >> 2) + 4 * hi; }
; __device__ __forceinline__ int crow(int r, int hi) { return (r & 3) + 8 * (r >> 2) + 4 * hi; }
; __device__ __forceinline__ void attn_body256(const bf16_t* __restrict__ Qb, const bf16_t* __restrict__ Kh, const bf16_t* __restrict__ Vh,
;                                              bf16_t* Ob, int seq, unsigned char* lds, float lam, int MODE, bf16_t* Ab, const float* wsub) {
;     ...
;     for (int r = 0; r < 16; ++r) { const int orow = crow(r, hi); float ss = 0.f;
; #pragma unroll
;       for (int d0 = 0; d0 < 8; ++d0) { const float v = bf2f(Ow[(long)orow * LDO + d0 * 32 + r32]) - lam * (o[d0][r] * rli[r]); o[d0][r] = v; ss += v * v; }
	v_lshlrev_b32_e32 v211, 16, v150
	v_mul_f32_e32 v50, v50, v198
	v_fma_f32 v50, -v218, v50, v211
	v_fmac_f32_e32 v200, v50, v50
	v_and_b32_e32 v211, 0xffff0000, v150
	v_mul_f32_e32 v51, v51, v198
	v_fma_f32 v51, -v218, v51, v211
	v_fmac_f32_e32 v200, v51, v51
	v_lshlrev_b32_e32 v211, 16, v151
	v_mul_f32_e32 v52, v52, v198
	v_fma_f32 v52, -v218, v52, v211
	v_fmac_f32_e32 v200, v52, v52
	v_and_b32_e32 v211, 0xffff0000, v151
	v_mul_f32_e32 v53, v53, v198
	v_fma_f32 v53, -v218, v53, v211
	v_fmac_f32_e32 v200, v53, v53
	s_waitcnt vmcnt(20)
	v_lshlrev_b32_e32 v211, 16, v152
	v_mul_f32_e32 v58, v58, v198
	v_fma_f32 v58, -v218, v58, v211
	v_fmac_f32_e32 v200, v58, v58
	v_and_b32_e32 v211, 0xffff0000, v152
	v_mul_f32_e32 v59, v59, v198
	v_fma_f32 v59, -v218, v59, v211
	v_fmac_f32_e32 v200, v59, v59
	v_lshlrev_b32_e32 v211, 16, v153
	v_mul_f32_e32 v60, v60, v198
	v_fma_f32 v60, -v218, v60, v211
	v_fmac_f32_e32 v200, v60, v60
	v_and_b32_e32 v211, 0xffff0000, v153
	v_mul_f32_e32 v61, v61, v198
	v_fma_f32 v61, -v218, v61, v211
	v_fmac_f32_e32 v200, v61, v61
	s_waitcnt vmcnt(19)
	v_lshlrev_b32_e32 v211, 16, v154
	v_mul_f32_e32 v34, v34, v198
	v_fma_f32 v34, -v218, v34, v211
	v_fmac_f32_e32 v200, v34, v34
	v_and_b32_e32 v211, 0xffff0000, v154
	v_mul_f32_e32 v35, v35, v198
	v_fma_f32 v35, -v218, v35, v211
	v_fmac_f32_e32 v200, v35, v35
	v_lshlrev_b32_e32 v211, 16, v155
	v_mul_f32_e32 v36, v36, v198
	v_fma_f32 v36, -v218, v36, v211
	v_fmac_f32_e32 v200, v36, v36
	v_and_b32_e32 v211, 0xffff0000, v155
	v_mul_f32_e32 v37, v37, v198
	v_fma_f32 v37, -v218, v37, v211
	v_fmac_f32_e32 v200, v37, v37
	s_waitcnt vmcnt(18)
	v_lshlrev_b32_e32 v211, 16, v156
	v_mul_f32_e32 v42, v42, v198
	v_fma_f32 v42, -v218, v42, v211
	v_fmac_f32_e32 v200, v42, v42
	v_and_b32_e32 v211, 0xffff0000, v156
	v_mul_f32_e32 v43, v43, v198
	v_fma_f32 v43, -v218, v43, v211
	v_fmac_f32_e32 v200, v43, v43
	v_lshlrev_b32_e32 v211, 16, v157
	v_mul_f32_e32 v44, v44, v198
	v_fma_f32 v44, -v218, v44, v211
	v_fmac_f32_e32 v200, v44, v44
	v_and_b32_e32 v211, 0xffff0000, v157
	v_mul_f32_e32 v45, v45, v198
	v_fma_f32 v45, -v218, v45, v211
	v_fmac_f32_e32 v200, v45, v45
	s_waitcnt vmcnt(17)
	v_lshlrev_b32_e32 v211, 16, v158
	v_mul_f32_e32 v18, v18, v198
	v_fma_f32 v18, -v218, v18, v211
	v_fmac_f32_e32 v200, v18, v18
	v_and_b32_e32 v211, 0xffff0000, v158
	v_mul_f32_e32 v19, v19, v198
	v_fma_f32 v19, -v218, v19, v211
	v_fmac_f32_e32 v200, v19, v19
	v_lshlrev_b32_e32 v211, 16, v159
	v_mul_f32_e32 v20, v20, v198
	v_fma_f32 v20, -v218, v20, v211
	v_fmac_f32_e32 v200, v20, v20
	v_and_b32_e32 v211, 0xffff0000, v159
	v_mul_f32_e32 v21, v21, v198
	v_fma_f32 v21, -v218, v21, v211
	v_fmac_f32_e32 v200, v21, v21
	s_waitcnt vmcnt(16)
	v_lshlrev_b32_e32 v211, 16, v160
	v_mul_f32_e32 v26, v26, v198
	v_fma_f32 v26, -v218, v26, v211
	v_fmac_f32_e32 v200, v26, v26
	v_and_b32_e32 v211, 0xffff0000, v160
	v_mul_f32_e32 v27, v27, v198
	v_fma_f32 v27, -v218, v27, v211
	v_fmac_f32_e32 v200, v27, v27
	v_lshlrev_b32_e32 v211, 16, v161
	v_mul_f32_e32 v28, v28, v198
	v_fma_f32 v28, -v218, v28, v211
	v_fmac_f32_e32 v200, v28, v28
	v_and_b32_e32 v211, 0xffff0000, v161
	v_mul_f32_e32 v29, v29, v198
	v_fma_f32 v29, -v218, v29, v211
	v_fmac_f32_e32 v200, v29, v29
	s_waitcnt vmcnt(15)
	v_lshlrev_b32_e32 v211, 16, v162
	v_mul_f32_e32 v6, v6, v199
	v_fma_f32 v6, -v218, v6, v211
	v_fmac_f32_e32 v201, v6, v6
	v_and_b32_e32 v211, 0xffff0000, v162
	v_mul_f32_e32 v7, v7, v199
	v_fma_f32 v7, -v218, v7, v211
	v_fmac_f32_e32 v201, v7, v7
	v_lshlrev_b32_e32 v211, 16, v163
	v_mul_f32_e32 v8, v8, v199
	v_fma_f32 v8, -v218, v8, v211
	v_fmac_f32_e32 v201, v8, v8
	v_and_b32_e32 v211, 0xffff0000, v163
	v_mul_f32_e32 v9, v9, v199
	v_fma_f32 v9, -v218, v9, v211
	v_fmac_f32_e32 v201, v9, v9
	s_waitcnt vmcnt(14)
	v_lshlrev_b32_e32 v211, 16, v164
	v_mul_f32_e32 v14, v14, v199
	v_fma_f32 v14, -v218, v14, v211
	v_fmac_f32_e32 v201, v14, v14
	v_and_b32_e32 v211, 0xffff0000, v164
	v_mul_f32_e32 v15, v15, v199
	v_fma_f32 v15, -v218, v15, v211
	v_fmac_f32_e32 v201, v15, v15
	v_lshlrev_b32_e32 v211, 16, v165
	v_mul_f32_e32 v16, v16, v199
	v_fma_f32 v16, -v218, v16, v211
	v_fmac_f32_e32 v201, v16, v16
	v_and_b32_e32 v211, 0xffff0000, v165
	v_mul_f32_e32 v17, v17, v199
	v_fma_f32 v17, -v218, v17, v211
	v_fmac_f32_e32 v201, v17, v17
	s_waitcnt vmcnt(13)
	v_lshlrev_b32_e32 v211, 16, v166
	v_mul_f32_e32 v118, v118, v199
	v_fma_f32 v118, -v218, v118, v211
	v_fmac_f32_e32 v201, v118, v118
	v_and_b32_e32 v211, 0xffff0000, v166
	v_mul_f32_e32 v119, v119, v199
	v_fma_f32 v119, -v218, v119, v211
	v_fmac_f32_e32 v201, v119, v119
	v_lshlrev_b32_e32 v211, 16, v167
	v_mul_f32_e32 v120, v120, v199
	v_fma_f32 v120, -v218, v120, v211
	v_fmac_f32_e32 v201, v120, v120
	v_and_b32_e32 v211, 0xffff0000, v167
	v_mul_f32_e32 v121, v121, v199
	v_fma_f32 v121, -v218, v121, v211
	v_fmac_f32_e32 v201, v121, v121
	s_waitcnt vmcnt(12)
	v_lshlrev_b32_e32 v211, 16, v168
	v_mul_f32_e32 v126, v126, v199
	v_fma_f32 v126, -v218, v126, v211
	v_fmac_f32_e32 v201, v126, v126
	v_and_b32_e32 v211, 0xffff0000, v168
	v_mul_f32_e32 v127, v127, v199
	v_fma_f32 v127, -v218, v127, v211
	v_fmac_f32_e32 v201, v127, v127
	v_lshlrev_b32_e32 v211, 16, v169
	v_mul_f32_e32 v128, v128, v199
	v_fma_f32 v128, -v218, v128, v211
	v_fmac_f32_e32 v201, v128, v128
	v_and_b32_e32 v211, 0xffff0000, v169
	v_mul_f32_e32 v129, v129, v199
	v_fma_f32 v129, -v218, v129, v211
	v_fmac_f32_e32 v201, v129, v129
	s_waitcnt vmcnt(11)
; __device__ __forceinline__ float bf2f(bf16_t b) { return __uint_as_float(((unsigned)b) << 16); }
; __device__ __forceinline__ int crow(int r, int hi) { return (r & 3) + 8 * (r >> 2) + 4 * hi; }
; __device__ __forceinline__ int crow(int r, int hi) { return (r & 3) + 8 * (r >> 2) + 4 * hi; }
; __device__ __forceinline__ void attn_body256(const bf16_t* __restrict__ Qb, const bf16_t* __restrict__ Kh, const bf16_t* __restrict__ Vh,
;                                              bf16_t* Ob, int seq, unsigned char* lds, float lam, int MODE, bf16_t* Ab, const float* wsub) {
;     ...
;     for (int r = 0; r < 16; ++r) { const int orow = crow(r, hi); float ss = 0.f;
; #pragma unroll
;       for (int d0 = 0; d0 < 8; ++d0) { const float v = bf2f(Ow[(long)orow * LDO + d0 * 32 + r32]) - lam * (o[d0][r] * rli[r]); o[d0][r] = v; ss += v * v; }
	v_lshlrev_b32_e32 v211, 16, v170
	v_mul_f32_e32 v102, v102, v199
	v_fma_f32 v102, -v218, v102, v211
	v_fmac_f32_e32 v201, v102, v102
	v_and_b32_e32 v211, 0xffff0000, v170
	v_mul_f32_e32 v103, v103, v199
	v_fma_f32 v103, -v218, v103, v211
	v_fmac_f32_e32 v201, v103, v103
	v_lshlrev_b32_e32 v211, 16, v171
	v_mul_f32_e32 v104, v104, v199
	v_fma_f32 v104, -v218, v104, v211
	v_fmac_f32_e32 v201, v104, v104
	v_and_b32_e32 v211, 0xffff0000, v171
	v_mul_f32_e32 v105, v105, v199
	v_fma_f32 v105, -v218, v105, v211
	v_fmac_f32_e32 v201, v105, v105
	s_waitcnt vmcnt(10)
	v_lshlrev_b32_e32 v211, 16, v172
	v_mul_f32_e32 v110, v110, v199
	v_fma_f32 v110, -v218, v110, v211
	v_fmac_f32_e32 v201, v110, v110
	v_and_b32_e32 v211, 0xffff0000, v172
	v_mul_f32_e32 v111, v111, v199
	v_fma_f32 v111, -v218, v111, v211
	v_fmac_f32_e32 v201, v111, v111
	v_lshlrev_b32_e32 v211, 16, v173
	v_mul_f32_e32 v112, v112, v199
	v_fma_f32 v112, -v218, v112, v211
	v_fmac_f32_e32 v201, v112, v112
	v_and_b32_e32 v211, 0xffff0000, v173
	v_mul_f32_e32 v113, v113, v199
	v_fma_f32 v113, -v218, v113, v211
	v_fmac_f32_e32 v201, v113, v113
	s_waitcnt vmcnt(9)
	v_lshlrev_b32_e32 v211, 16, v174
	v_mul_f32_e32 v86, v86, v199
	v_fma_f32 v86, -v218, v86, v211
	v_fmac_f32_e32 v201, v86, v86
	v_and_b32_e32 v211, 0xffff0000, v174
	v_mul_f32_e32 v87, v87, v199
	v_fma_f32 v87, -v218, v87, v211
	v_fmac_f32_e32 v201, v87, v87
	v_lshlrev_b32_e32 v211, 16, v175
	v_mul_f32_e32 v88, v88, v199
	v_fma_f32 v88, -v218, v88, v211
	v_fmac_f32_e32 v201, v88, v88
	v_and_b32_e32 v211, 0xffff0000, v175
	v_mul_f32_e32 v89, v89, v199
	v_fma_f32 v89, -v218, v89, v211
	v_fmac_f32_e32 v201, v89, v89
	s_waitcnt vmcnt(8)
	v_lshlrev_b32_e32 v211, 16, v176
	v_mul_f32_e32 v94, v94, v199
	v_fma_f32 v94, -v218, v94, v211
	v_fmac_f32_e32 v201, v94, v94
	v_and_b32_e32 v211, 0xffff0000, v176
	v_mul_f32_e32 v95, v95, v199
	v_fma_f32 v95, -v218, v95, v211
	v_fmac_f32_e32 v201, v95, v95
	v_lshlrev_b32_e32 v211, 16, v177
	v_mul_f32_e32 v96, v96, v199
	v_fma_f32 v96, -v218, v96, v211
	v_fmac_f32_e32 v201, v96, v96
	v_and_b32_e32 v211, 0xffff0000, v177
	v_mul_f32_e32 v97, v97, v199
	v_fma_f32 v97, -v218, v97, v211
	v_fmac_f32_e32 v201, v97, v97
	s_waitcnt vmcnt(7)
	v_lshlrev_b32_e32 v211, 16, v178
	v_mul_f32_e32 v70, v70, v199
	v_fma_f32 v70, -v218, v70, v211
	v_fmac_f32_e32 v201, v70, v70
	v_and_b32_e32 v211, 0xffff0000, v178
	v_mul_f32_e32 v71, v71, v199
	v_fma_f32 v71, -v218, v71, v211
	v_fmac_f32_e32 v201, v71, v71
	v_lshlrev_b32_e32 v211, 16, v179
	v_mul_f32_e32 v72, v72, v199
	v_fma_f32 v72, -v218, v72, v211
	v_fmac_f32_e32 v201, v72, v72
	v_and_b32_e32 v211, 0xffff0000, v179
	v_mul_f32_e32 v73, v73, v199
	v_fma_f32 v73, -v218, v73, v211
	v_fmac_f32_e32 v201, v73, v73
	s_waitcnt vmcnt(6)
	v_lshlrev_b32_e32 v211, 16, v180
	v_mul_f32_e32 v78, v78, v199
	v_fma_f32 v78, -v218, v78, v211
	v_fmac_f32_e32 v201, v78, v78
	v_and_b32_e32 v211, 0xffff0000, v180
	v_mul_f32_e32 v79, v79, v199
	v_fma_f32 v79, -v218, v79, v211
	v_fmac_f32_e32 v201, v79, v79
	v_lshlrev_b32_e32 v211, 16, v181
	v_mul_f32_e32 v80, v80, v199
	v_fma_f32 v80, -v218, v80, v211
	v_fmac_f32_e32 v201, v80, v80
	v_and_b32_e32 v211, 0xffff0000, v181
	v_mul_f32_e32 v81, v81, v199
	v_fma_f32 v81, -v218, v81, v211
	v_fmac_f32_e32 v201, v81, v81
	s_waitcnt vmcnt(5)
	v_lshlrev_b32_e32 v211, 16, v182
	v_mul_f32_e32 v54, v54, v199
	v_fma_f32 v54, -v218, v54, v211
	v_fmac_f32_e32 v201, v54, v54
	v_and_b32_e32 v211, 0xffff0000, v182
	v_mul_f32_e32 v55, v55, v199
	v_fma_f32 v55, -v218, v55, v211
	v_fmac_f32_e32 v201, v55, v55
	v_lshlrev_b32_e32 v211, 16, v183
	v_mul_f32_e32 v56, v56, v199
	v_fma_f32 v56, -v218, v56, v211
	v_fmac_f32_e32 v201, v56, v56
	v_and_b32_e32 v211, 0xffff0000, v183
	v_mul_f32_e32 v57, v57, v199
	v_fma_f32 v57, -v218, v57, v211
	v_fmac_f32_e32 v201, v57, v57
	s_waitcnt vmcnt(4)
	v_lshlrev_b32_e32 v211, 16, v184
	v_mul_f32_e32 v62, v62, v199
	v_fma_f32 v62, -v218, v62, v211
	v_fmac_f32_e32 v201, v62, v62
	v_and_b32_e32 v211, 0xffff0000, v184
	v_mul_f32_e32 v63, v63, v199
	v_fma_f32 v63, -v218, v63, v211
	v_fmac_f32_e32 v201, v63, v63
	v_lshlrev_b32_e32 v211, 16, v185
	v_mul_f32_e32 v64, v64, v199
	v_fma_f32 v64, -v218, v64, v211
	v_fmac_f32_e32 v201, v64, v64
	v_and_b32_e32 v211, 0xffff0000, v185
	v_mul_f32_e32 v65, v65, v199
	v_fma_f32 v65, -v218, v65, v211
	v_fmac_f32_e32 v201, v65, v65
	s_waitcnt vmcnt(3)
	v_lshlrev_b32_e32 v211, 16, v186
	v_mul_f32_e32 v38, v38, v199
	v_fma_f32 v38, -v218, v38, v211
	v_fmac_f32_e32 v201, v38, v38
	v_and_b32_e32 v211, 0xffff0000, v186
	v_mul_f32_e32 v39, v39, v199
	v_fma_f32 v39, -v218, v39, v211
	v_fmac_f32_e32 v201, v39, v39
	v_lshlrev_b32_e32 v211, 16, v187
	v_mul_f32_e32 v40, v40, v199
	v_fma_f32 v40, -v218, v40, v211
	v_fmac_f32_e32 v201, v40, v40
	v_and_b32_e32 v211, 0xffff0000, v187
	v_mul_f32_e32 v41, v41, v199
	v_fma_f32 v41, -v218, v41, v211
	v_fmac_f32_e32 v201, v41, v41
	s_waitcnt vmcnt(2)
	v_lshlrev_b32_e32 v211, 16, v188
	v_mul_f32_e32 v46, v46, v199
	v_fma_f32 v46, -v218, v46, v211
	v_fmac_f32_e32 v201, v46, v46
	v_and_b32_e32 v211, 0xffff0000, v188
	v_mul_f32_e32 v47, v47, v199
	v_fma_f32 v47, -v218, v47, v211
	v_fmac_f32_e32 v201, v47, v47
	v_lshlrev_b32_e32 v211, 16, v189
	v_mul_f32_e32 v48, v48, v199
	v_fma_f32 v48, -v218, v48, v211
	v_fmac_f32_e32 v201, v48, v48
	v_and_b32_e32 v211, 0xffff0000, v189
	v_mul_f32_e32 v49, v49, v199
	v_fma_f32 v49, -v218, v49, v211
	v_fmac_f32_e32 v201, v49, v49
	s_waitcnt vmcnt(1)
; __device__ __forceinline__ bf16_t f2bf(float x) { return (bf16_t)(cvt_pk_bf16(x, x) & 0xffffu); }
; __device__ __forceinline__ float bf2f(bf16_t b) { return __uint_as_float(((unsigned)b) << 16); }
; __device__ __forceinline__ int crow(int r, int hi) { return (r & 3) + 8 * (r >> 2) + 4 * hi; }
; __device__ __forceinline__ int crow(int r, int hi) { return (r & 3) + 8 * (r >> 2) + 4 * hi; }
; __device__ __forceinline__ void attn_body256(const bf16_t* __restrict__ Qb, const bf16_t* __restrict__ Kh, const bf16_t* __restrict__ Vh,
;                                              bf16_t* Ob, int seq, unsigned char* lds, float lam, int MODE, bf16_t* Ab, const float* wsub) {
;     ...
;     for (int d0 = 0; d0 < 8; ++d0) wv[d0] = wsub[d0 * 32 + r32] * (1.f - LAMBDA_INIT);
; #pragma unroll
;     for (int r = 0; r < 16; ++r) { const int orow = crow(r, hi); float ss = 0.f;
; #pragma unroll
;       for (int d0 = 0; d0 < 8; ++d0) { const float v = bf2f(Ow[(long)orow * LDO + d0 * 32 + r32]) - lam * (o[d0][r] * rli[r]); o[d0][r] = v; ss += v * v; }
;       ss += __shfl_xor(ss, 1, 64); ss += __shfl_xor(ss, 2, 64); ss += __shfl_xor(ss, 4, 64); ss += __shfl_xor(ss, 8, 64); ss += __shfl_xor(ss, 16, 64);
;       const float rstd = rsqrtf(ss * (1.f / 256.f) + NORM_EPS);
; #pragma unroll
;       for (int d0 = 0; d0 < 8; ++d0) Aw[(long)orow * LDO + d0 * 32 + r32] = f2bf(o[d0][r] * rstd * wv[d0]); }
	v_lshlrev_b32_e32 v211, 16, v190
	v_mul_f32_e32 v22, v22, v199
	v_fma_f32 v22, -v218, v22, v211
	v_fmac_f32_e32 v201, v22, v22
	v_and_b32_e32 v211, 0xffff0000, v190
	v_mul_f32_e32 v23, v23, v199
	v_fma_f32 v23, -v218, v23, v211
	v_fmac_f32_e32 v201, v23, v23
	v_lshlrev_b32_e32 v211, 16, v191
	v_mul_f32_e32 v24, v24, v199
	v_fma_f32 v24, -v218, v24, v211
	v_fmac_f32_e32 v201, v24, v24
	v_and_b32_e32 v211, 0xffff0000, v191
	v_mul_f32_e32 v25, v25, v199
	v_fma_f32 v25, -v218, v25, v211
	v_fmac_f32_e32 v201, v25, v25
	s_waitcnt vmcnt(0)
	v_lshlrev_b32_e32 v211, 16, v192
	v_mul_f32_e32 v30, v30, v199
	v_fma_f32 v30, -v218, v30, v211
	v_fmac_f32_e32 v201, v30, v30
	v_and_b32_e32 v211, 0xffff0000, v192
	v_mul_f32_e32 v31, v31, v199
	v_fma_f32 v31, -v218, v31, v211
	v_fmac_f32_e32 v201, v31, v31
	v_lshlrev_b32_e32 v211, 16, v193
	v_mul_f32_e32 v32, v32, v199
	v_fma_f32 v32, -v218, v32, v211
	v_fmac_f32_e32 v201, v32, v32
	v_and_b32_e32 v211, 0xffff0000, v193
	v_mul_f32_e32 v33, v33, v199
	v_fma_f32 v33, -v218, v33, v211
	v_fmac_f32_e32 v201, v33, v33
	v_mov_b32_e32 v212, v200
	v_mov_b32_e32 v213, v201
	s_nop 1
	v_permlane32_swap_b32_e32 v200, v212
	v_permlane32_swap_b32_e32 v201, v213
	v_add_f32_e32 v200, v200, v212
	v_add_f32_e32 v201, v201, v213
	v_mov_b32_e32 v212, v200
	v_mov_b32_e32 v213, v201
	s_nop 1
	v_permlane16_swap_b32_e32 v200, v212
	v_permlane16_swap_b32_e32 v201, v213
	v_add_f32_e32 v200, v200, v212
	v_add_f32_e32 v201, v201, v213
	v_mul_f32_e32 v200, 0x3b800000, v200
	v_add_f32_e32 v200, 0x3727c5ac, v200
	v_mul_f32_e32 v201, 0x3b800000, v201
	v_add_f32_e32 v201, 0x3727c5ac, v201
	v_rsq_f32_e32 v200, v200
	v_rsq_f32_e32 v201, v201
	s_nop 0
	v_mul_f32_e32 v200, 0x3f24fd5c, v200
	v_mul_f32_e32 v201, 0x3f24fd5c, v201
	global_load_dwordx4 v[130:133], v210, s[28:29]
	global_load_dwordx4 v[134:137], v210, s[28:29] offset:64
	global_load_dwordx4 v[138:141], v210, s[28:29] offset:128
	global_load_dwordx4 v[142:145], v210, s[28:29] offset:192
	s_waitcnt vmcnt(3)
	v_mul_f32_e32 v2, v2, v200
	v_mul_f32_e32 v2, v2, v130
	v_mul_f32_e32 v3, v3, v200
	v_mul_f32_e32 v3, v3, v131
	v_mul_f32_e32 v4, v4, v200
	v_mul_f32_e32 v4, v4, v132
	v_mul_f32_e32 v5, v5, v200
	v_mul_f32_e32 v5, v5, v133
	v_cvt_pk_bf16_f32 v2, v2, v3
	v_cvt_pk_bf16_f32 v3, v4, v5
	global_store_dwordx2 v[204:205], v[2:3], off
	v_mul_f32_e32 v6, v6, v201
	v_mul_f32_e32 v6, v6, v130
	v_mul_f32_e32 v7, v7, v201
	v_mul_f32_e32 v7, v7, v131
	v_mul_f32_e32 v8, v8, v201
	v_mul_f32_e32 v8, v8, v132
	v_mul_f32_e32 v9, v9, v201
	v_mul_f32_e32 v9, v9, v133
	v_cvt_pk_bf16_f32 v6, v6, v7
	v_cvt_pk_bf16_f32 v7, v8, v9
	global_store_dwordx2 v[206:207], v[6:7], off
	s_waitcnt vmcnt(2)
	v_mul_f32_e32 v10, v10, v200
	v_mul_f32_e32 v10, v10, v134
	v_mul_f32_e32 v11, v11, v200
	v_mul_f32_e32 v11, v11, v135
	v_mul_f32_e32 v12, v12, v200
	v_mul_f32_e32 v12, v12, v136
	v_mul_f32_e32 v13, v13, v200
	v_mul_f32_e32 v13, v13, v137
	v_cvt_pk_bf16_f32 v10, v10, v11
	v_cvt_pk_bf16_f32 v11, v12, v13
	global_store_dwordx2 v[204:205], v[10:11], off offset:32
	v_mul_f32_e32 v14, v14, v201
	v_mul_f32_e32 v14, v14, v134
	v_mul_f32_e32 v15, v15, v201
	v_mul_f32_e32 v15, v15, v135
	v_mul_f32_e32 v16, v16, v201
	v_mul_f32_e32 v16, v16, v136
	v_mul_f32_e32 v17, v17, v201
	v_mul_f32_e32 v17, v17, v137
	v_cvt_pk_bf16_f32 v14, v14, v15
	v_cvt_pk_bf16_f32 v15, v16, v17
	global_store_dwordx2 v[206:207], v[14:15], off offset:32
	s_waitcnt vmcnt(1)
	v_mul_f32_e32 v114, v114, v200
	v_mul_f32_e32 v114, v114, v138
	v_mul_f32_e32 v115, v115, v200
	v_mul_f32_e32 v115, v115, v139
	v_mul_f32_e32 v116, v116, v200
	v_mul_f32_e32 v116, v116, v140
	v_mul_f32_e32 v117, v117, v200
	v_mul_f32_e32 v117, v117, v141
	v_cvt_pk_bf16_f32 v114, v114, v115
	v_cvt_pk_bf16_f32 v115, v116, v117
	global_store_dwordx2 v[204:205], v[114:115], off offset:64
	v_mul_f32_e32 v118, v118, v201
	v_mul_f32_e32 v118, v118, v138
	v_mul_f32_e32 v119, v119, v201
	v_mul_f32_e32 v119, v119, v139
	v_mul_f32_e32 v120, v120, v201
	v_mul_f32_e32 v120, v120, v140
	v_mul_f32_e32 v121, v121, v201
	v_mul_f32_e32 v121, v121, v141
	v_cvt_pk_bf16_f32 v118, v118, v119
	v_cvt_pk_bf16_f32 v119, v120, v121
	global_store_dwordx2 v[206:207], v[118:119], off offset:64
	s_waitcnt vmcnt(0)
	v_mul_f32_e32 v122, v122, v200
	v_mul_f32_e32 v122, v122, v142
	v_mul_f32_e32 v123, v123, v200
	v_mul_f32_e32 v123, v123, v143
	v_mul_f32_e32 v124, v124, v200
	v_mul_f32_e32 v124, v124, v144
	v_mul_f32_e32 v125, v125, v200
	v_mul_f32_e32 v125, v125, v145
	v_cvt_pk_bf16_f32 v122, v122, v123
	v_cvt_pk_bf16_f32 v123, v124, v125
	global_store_dwordx2 v[204:205], v[122:123], off offset:96
	v_mul_f32_e32 v126, v126, v201
	v_mul_f32_e32 v126, v126, v142
	v_mul_f32_e32 v127, v127, v201
	v_mul_f32_e32 v127, v127, v143
	v_mul_f32_e32 v128, v128, v201
	v_mul_f32_e32 v128, v128, v144
	v_mul_f32_e32 v129, v129, v201
	v_mul_f32_e32 v129, v129, v145
	v_cvt_pk_bf16_f32 v126, v126, v127
	v_cvt_pk_bf16_f32 v127, v128, v129
	global_store_dwordx2 v[206:207], v[126:127], off offset:96
	global_load_dwordx4 v[130:133], v210, s[28:29] offset:256
	global_load_dwordx4 v[134:137], v210, s[28:29] offset:320
	global_load_dwordx4 v[138:141], v210, s[28:29] offset:384
	global_load_dwordx4 v[142:145], v210, s[28:29] offset:448
	s_waitcnt vmcnt(3)
; __device__ __forceinline__ bf16_t f2bf(float x) { return (bf16_t)(cvt_pk_bf16(x, x) & 0xffffu); }
; __device__ __forceinline__ float bf2f(bf16_t b) { return __uint_as_float(((unsigned)b) << 16); }
; __device__ __forceinline__ int crow(int r, int hi) { return (r & 3) + 8 * (r >> 2) + 4 * hi; }
; __device__ __forceinline__ int crow(int r, int hi) { return (r & 3) + 8 * (r >> 2) + 4 * hi; }
; __device__ __forceinline__ void attn_body256(const bf16_t* __restrict__ Qb, const bf16_t* __restrict__ Kh, const bf16_t* __restrict__ Vh,
;                                              bf16_t* Ob, int seq, unsigned char* lds, float lam, int MODE, bf16_t* Ab, const float* wsub) {
;     ...
;     for (int d0 = 0; d0 < 8; ++d0) wv[d0] = wsub[d0 * 32 + r32] * (1.f - LAMBDA_INIT);
; #pragma unroll
;     for (int r = 0; r < 16; ++r) { const int orow = crow(r, hi); float ss = 0.f;
; #pragma unroll
;       for (int d0 = 0; d0 < 8; ++d0) { const float v = bf2f(Ow[(long)orow * LDO + d0 * 32 + r32]) - lam * (o[d0][r] * rli[r]); o[d0][r] = v; ss += v * v; }
;       ss += __shfl_xor(ss, 1, 64); ss += __shfl_xor(ss, 2, 64); ss += __shfl_xor(ss, 4, 64); ss += __shfl_xor(ss, 8, 64); ss += __shfl_xor(ss, 16, 64);
;       const float rstd = rsqrtf(ss * (1.f / 256.f) + NORM_EPS);
; #pragma unroll
;       for (int d0 = 0; d0 < 8; ++d0) Aw[(long)orow * LDO + d0 * 32 + r32] = f2bf(o[d0][r] * rstd * wv[d0]); }
	v_mul_f32_e32 v98, v98, v200
	v_mul_f32_e32 v98, v98, v130
	v_mul_f32_e32 v99, v99, v200
	v_mul_f32_e32 v99, v99, v131
	v_mul_f32_e32 v100, v100, v200
	v_mul_f32_e32 v100, v100, v132
	v_mul_f32_e32 v101, v101, v200
	v_mul_f32_e32 v101, v101, v133
	v_cvt_pk_bf16_f32 v98, v98, v99
	v_cvt_pk_bf16_f32 v99, v100, v101
	global_store_dwordx2 v[204:205], v[98:99], off offset:128
	v_mul_f32_e32 v102, v102, v201
	v_mul_f32_e32 v102, v102, v130
	v_mul_f32_e32 v103, v103, v201
	v_mul_f32_e32 v103, v103, v131
	v_mul_f32_e32 v104, v104, v201
	v_mul_f32_e32 v104, v104, v132
	v_mul_f32_e32 v105, v105, v201
	v_mul_f32_e32 v105, v105, v133
	v_cvt_pk_bf16_f32 v102, v102, v103
	v_cvt_pk_bf16_f32 v103, v104, v105
	global_store_dwordx2 v[206:207], v[102:103], off offset:128
	s_waitcnt vmcnt(2)
	v_mul_f32_e32 v106, v106, v200
	v_mul_f32_e32 v106, v106, v134
	v_mul_f32_e32 v107, v107, v200
	v_mul_f32_e32 v107, v107, v135
	v_mul_f32_e32 v108, v108, v200
	v_mul_f32_e32 v108, v108, v136
	v_mul_f32_e32 v109, v109, v200
	v_mul_f32_e32 v109, v109, v137
	v_cvt_pk_bf16_f32 v106, v106, v107
	v_cvt_pk_bf16_f32 v107, v108, v109
	global_store_dwordx2 v[204:205], v[106:107], off offset:160
	v_mul_f32_e32 v110, v110, v201
	v_mul_f32_e32 v110, v110, v134
	v_mul_f32_e32 v111, v111, v201
	v_mul_f32_e32 v111, v111, v135
	v_mul_f32_e32 v112, v112, v201
	v_mul_f32_e32 v112, v112, v136
	v_mul_f32_e32 v113, v113, v201
	v_mul_f32_e32 v113, v113, v137
	v_cvt_pk_bf16_f32 v110, v110, v111
	v_cvt_pk_bf16_f32 v111, v112, v113
	global_store_dwordx2 v[206:207], v[110:111], off offset:160
	s_waitcnt vmcnt(1)
	v_mul_f32_e32 v82, v82, v200
	v_mul_f32_e32 v82, v82, v138
	v_mul_f32_e32 v83, v83, v200
	v_mul_f32_e32 v83, v83, v139
	v_mul_f32_e32 v84, v84, v200
	v_mul_f32_e32 v84, v84, v140
	v_mul_f32_e32 v85, v85, v200
	v_mul_f32_e32 v85, v85, v141
	v_cvt_pk_bf16_f32 v82, v82, v83
	v_cvt_pk_bf16_f32 v83, v84, v85
	global_store_dwordx2 v[204:205], v[82:83], off offset:192
	v_mul_f32_e32 v86, v86, v201
	v_mul_f32_e32 v86, v86, v138
	v_mul_f32_e32 v87, v87, v201
	v_mul_f32_e32 v87, v87, v139
	v_mul_f32_e32 v88, v88, v201
	v_mul_f32_e32 v88, v88, v140
	v_mul_f32_e32 v89, v89, v201
	v_mul_f32_e32 v89, v89, v141
	v_cvt_pk_bf16_f32 v86, v86, v87
	v_cvt_pk_bf16_f32 v87, v88, v89
	global_store_dwordx2 v[206:207], v[86:87], off offset:192
	s_waitcnt vmcnt(0)
	v_mul_f32_e32 v90, v90, v200
	v_mul_f32_e32 v90, v90, v142
	v_mul_f32_e32 v91, v91, v200
	v_mul_f32_e32 v91, v91, v143
	v_mul_f32_e32 v92, v92, v200
	v_mul_f32_e32 v92, v92, v144
	v_mul_f32_e32 v93, v93, v200
	v_mul_f32_e32 v93, v93, v145
	v_cvt_pk_bf16_f32 v90, v90, v91
	v_cvt_pk_bf16_f32 v91, v92, v93
	global_store_dwordx2 v[204:205], v[90:91], off offset:224
	v_mul_f32_e32 v94, v94, v201
	v_mul_f32_e32 v94, v94, v142
	v_mul_f32_e32 v95, v95, v201
	v_mul_f32_e32 v95, v95, v143
	v_mul_f32_e32 v96, v96, v201
	v_mul_f32_e32 v96, v96, v144
	v_mul_f32_e32 v97, v97, v201
	v_mul_f32_e32 v97, v97, v145
	v_cvt_pk_bf16_f32 v94, v94, v95
	v_cvt_pk_bf16_f32 v95, v96, v97
	global_store_dwordx2 v[206:207], v[94:95], off offset:224
	global_load_dwordx4 v[130:133], v210, s[28:29] offset:512
	global_load_dwordx4 v[134:137], v210, s[28:29] offset:576
	global_load_dwordx4 v[138:141], v210, s[28:29] offset:640
	global_load_dwordx4 v[142:145], v210, s[28:29] offset:704
	s_waitcnt vmcnt(3)
	v_mul_f32_e32 v66, v66, v200
	v_mul_f32_e32 v66, v66, v130
	v_mul_f32_e32 v67, v67, v200
	v_mul_f32_e32 v67, v67, v131
	v_mul_f32_e32 v68, v68, v200
	v_mul_f32_e32 v68, v68, v132
	v_mul_f32_e32 v69, v69, v200
	v_mul_f32_e32 v69, v69, v133
	v_cvt_pk_bf16_f32 v66, v66, v67
	v_cvt_pk_bf16_f32 v67, v68, v69
	global_store_dwordx2 v[204:205], v[66:67], off offset:256
	v_mul_f32_e32 v70, v70, v201
	v_mul_f32_e32 v70, v70, v130
	v_mul_f32_e32 v71, v71, v201
	v_mul_f32_e32 v71, v71, v131
	v_mul_f32_e32 v72, v72, v201
	v_mul_f32_e32 v72, v72, v132
	v_mul_f32_e32 v73, v73, v201
	v_mul_f32_e32 v73, v73, v133
	v_cvt_pk_bf16_f32 v70, v70, v71
	v_cvt_pk_bf16_f32 v71, v72, v73
	global_store_dwordx2 v[206:207], v[70:71], off offset:256
	s_waitcnt vmcnt(2)
	v_mul_f32_e32 v74, v74, v200
	v_mul_f32_e32 v74, v74, v134
	v_mul_f32_e32 v75, v75, v200
	v_mul_f32_e32 v75, v75, v135
	v_mul_f32_e32 v76, v76, v200
	v_mul_f32_e32 v76, v76, v136
	v_mul_f32_e32 v77, v77, v200
	v_mul_f32_e32 v77, v77, v137
	v_cvt_pk_bf16_f32 v74, v74, v75
	v_cvt_pk_bf16_f32 v75, v76, v77
	global_store_dwordx2 v[204:205], v[74:75], off offset:288
	v_mul_f32_e32 v78, v78, v201
	v_mul_f32_e32 v78, v78, v134
	v_mul_f32_e32 v79, v79, v201
	v_mul_f32_e32 v79, v79, v135
	v_mul_f32_e32 v80, v80, v201
	v_mul_f32_e32 v80, v80, v136
	v_mul_f32_e32 v81, v81, v201
	v_mul_f32_e32 v81, v81, v137
	v_cvt_pk_bf16_f32 v78, v78, v79
	v_cvt_pk_bf16_f32 v79, v80, v81
	global_store_dwordx2 v[206:207], v[78:79], off offset:288
	s_waitcnt vmcnt(1)
; __device__ __forceinline__ bf16_t f2bf(float x) { return (bf16_t)(cvt_pk_bf16(x, x) & 0xffffu); }
; __device__ __forceinline__ float bf2f(bf16_t b) { return __uint_as_float(((unsigned)b) << 16); }
; __device__ __forceinline__ int crow(int r, int hi) { return (r & 3) + 8 * (r >> 2) + 4 * hi; }
; __device__ __forceinline__ int crow(int r, int hi) { return (r & 3) + 8 * (r >> 2) + 4 * hi; }
; __device__ __forceinline__ void attn_body256(const bf16_t* __restrict__ Qb, const bf16_t* __restrict__ Kh, const bf16_t* __restrict__ Vh,
;                                              bf16_t* Ob, int seq, unsigned char* lds, float lam, int MODE, bf16_t* Ab, const float* wsub) {
;     ...
;     for (int d0 = 0; d0 < 8; ++d0) wv[d0] = wsub[d0 * 32 + r32] * (1.f - LAMBDA_INIT);
; #pragma unroll
;     for (int r = 0; r < 16; ++r) { const int orow = crow(r, hi); float ss = 0.f;
; #pragma unroll
;       for (int d0 = 0; d0 < 8; ++d0) { const float v = bf2f(Ow[(long)orow * LDO + d0 * 32 + r32]) - lam * (o[d0][r] * rli[r]); o[d0][r] = v; ss += v * v; }
;       ss += __shfl_xor(ss, 1, 64); ss += __shfl_xor(ss, 2, 64); ss += __shfl_xor(ss, 4, 64); ss += __shfl_xor(ss, 8, 64); ss += __shfl_xor(ss, 16, 64);
;       const float rstd = rsqrtf(ss * (1.f / 256.f) + NORM_EPS);
; #pragma unroll
;       for (int d0 = 0; d0 < 8; ++d0) Aw[(long)orow * LDO + d0 * 32 + r32] = f2bf(o[d0][r] * rstd * wv[d0]); }
	v_mul_f32_e32 v50, v50, v200
	v_mul_f32_e32 v50, v50, v138
	v_mul_f32_e32 v51, v51, v200
	v_mul_f32_e32 v51, v51, v139
	v_mul_f32_e32 v52, v52, v200
	v_mul_f32_e32 v52, v52, v140
	v_mul_f32_e32 v53, v53, v200
	v_mul_f32_e32 v53, v53, v141
	v_cvt_pk_bf16_f32 v50, v50, v51
	v_cvt_pk_bf16_f32 v51, v52, v53
	global_store_dwordx2 v[204:205], v[50:51], off offset:320
	v_mul_f32_e32 v54, v54, v201
	v_mul_f32_e32 v54, v54, v138
	v_mul_f32_e32 v55, v55, v201
	v_mul_f32_e32 v55, v55, v139
	v_mul_f32_e32 v56, v56, v201
	v_mul_f32_e32 v56, v56, v140
	v_mul_f32_e32 v57, v57, v201
	v_mul_f32_e32 v57, v57, v141
	v_cvt_pk_bf16_f32 v54, v54, v55
	v_cvt_pk_bf16_f32 v55, v56, v57
	global_store_dwordx2 v[206:207], v[54:55], off offset:320
	s_waitcnt vmcnt(0)
	v_mul_f32_e32 v58, v58, v200
	v_mul_f32_e32 v58, v58, v142
	v_mul_f32_e32 v59, v59, v200
	v_mul_f32_e32 v59, v59, v143
	v_mul_f32_e32 v60, v60, v200
	v_mul_f32_e32 v60, v60, v144
	v_mul_f32_e32 v61, v61, v200
	v_mul_f32_e32 v61, v61, v145
	v_cvt_pk_bf16_f32 v58, v58, v59
	v_cvt_pk_bf16_f32 v59, v60, v61
	global_store_dwordx2 v[204:205], v[58:59], off offset:352
	v_mul_f32_e32 v62, v62, v201
	v_mul_f32_e32 v62, v62, v142
	v_mul_f32_e32 v63, v63, v201
	v_mul_f32_e32 v63, v63, v143
	v_mul_f32_e32 v64, v64, v201
	v_mul_f32_e32 v64, v64, v144
	v_mul_f32_e32 v65, v65, v201
	v_mul_f32_e32 v65, v65, v145
	v_cvt_pk_bf16_f32 v62, v62, v63
	v_cvt_pk_bf16_f32 v63, v64, v65
	global_store_dwordx2 v[206:207], v[62:63], off offset:352
	global_load_dwordx4 v[130:133], v210, s[28:29] offset:768
	global_load_dwordx4 v[134:137], v210, s[28:29] offset:832
	global_load_dwordx4 v[138:141], v210, s[28:29] offset:896
	global_load_dwordx4 v[142:145], v210, s[28:29] offset:960
	s_waitcnt vmcnt(3)
	v_mul_f32_e32 v34, v34, v200
	v_mul_f32_e32 v34, v34, v130
	v_mul_f32_e32 v35, v35, v200
	v_mul_f32_e32 v35, v35, v131
	v_mul_f32_e32 v36, v36, v200
	v_mul_f32_e32 v36, v36, v132
	v_mul_f32_e32 v37, v37, v200
	v_mul_f32_e32 v37, v37, v133
	v_cvt_pk_bf16_f32 v34, v34, v35
	v_cvt_pk_bf16_f32 v35, v36, v37
	global_store_dwordx2 v[204:205], v[34:35], off offset:384
	v_mul_f32_e32 v38, v38, v201
	v_mul_f32_e32 v38, v38, v130
	v_mul_f32_e32 v39, v39, v201
	v_mul_f32_e32 v39, v39, v131
	v_mul_f32_e32 v40, v40, v201
	v_mul_f32_e32 v40, v40, v132
	v_mul_f32_e32 v41, v41, v201
	v_mul_f32_e32 v41, v41, v133
	v_cvt_pk_bf16_f32 v38, v38, v39
	v_cvt_pk_bf16_f32 v39, v40, v41
	global_store_dwordx2 v[206:207], v[38:39], off offset:384
	s_waitcnt vmcnt(2)
	v_mul_f32_e32 v42, v42, v200
	v_mul_f32_e32 v42, v42, v134
	v_mul_f32_e32 v43, v43, v200
	v_mul_f32_e32 v43, v43, v135
	v_mul_f32_e32 v44, v44, v200
	v_mul_f32_e32 v44, v44, v136
	v_mul_f32_e32 v45, v45, v200
	v_mul_f32_e32 v45, v45, v137
	v_cvt_pk_bf16_f32 v42, v42, v43
	v_cvt_pk_bf16_f32 v43, v44, v45
	global_store_dwordx2 v[204:205], v[42:43], off offset:416
	v_mul_f32_e32 v46, v46, v201
	v_mul_f32_e32 v46, v46, v134
	v_mul_f32_e32 v47, v47, v201
	v_mul_f32_e32 v47, v47, v135
	v_mul_f32_e32 v48, v48, v201
	v_mul_f32_e32 v48, v48, v136
	v_mul_f32_e32 v49, v49, v201
	v_mul_f32_e32 v49, v49, v137
	v_cvt_pk_bf16_f32 v46, v46, v47
	v_cvt_pk_bf16_f32 v47, v48, v49
	global_store_dwordx2 v[206:207], v[46:47], off offset:416
	s_waitcnt vmcnt(1)
	v_mul_f32_e32 v18, v18, v200
	v_mul_f32_e32 v18, v18, v138
	v_mul_f32_e32 v19, v19, v200
	v_mul_f32_e32 v19, v19, v139
	v_mul_f32_e32 v20, v20, v200
	v_mul_f32_e32 v20, v20, v140
	v_mul_f32_e32 v21, v21, v200
	v_mul_f32_e32 v21, v21, v141
	v_cvt_pk_bf16_f32 v18, v18, v19
	v_cvt_pk_bf16_f32 v19, v20, v21
	global_store_dwordx2 v[204:205], v[18:19], off offset:448
	v_mul_f32_e32 v22, v22, v201
	v_mul_f32_e32 v22, v22, v138
	v_mul_f32_e32 v23, v23, v201
	v_mul_f32_e32 v23, v23, v139
	v_mul_f32_e32 v24, v24, v201
	v_mul_f32_e32 v24, v24, v140
	v_mul_f32_e32 v25, v25, v201
	v_mul_f32_e32 v25, v25, v141
	v_cvt_pk_bf16_f32 v22, v22, v23
	v_cvt_pk_bf16_f32 v23, v24, v25
	global_store_dwordx2 v[206:207], v[22:23], off offset:448
	s_waitcnt vmcnt(0)
	v_mul_f32_e32 v26, v26, v200
	v_mul_f32_e32 v26, v26, v142
	v_mul_f32_e32 v27, v27, v200
	v_mul_f32_e32 v27, v27, v143
	v_mul_f32_e32 v28, v28, v200
	v_mul_f32_e32 v28, v28, v144
	v_mul_f32_e32 v29, v29, v200
	v_mul_f32_e32 v29, v29, v145
	v_cvt_pk_bf16_f32 v26, v26, v27
	v_cvt_pk_bf16_f32 v27, v28, v29
	global_store_dwordx2 v[204:205], v[26:27], off offset:480
	v_mul_f32_e32 v30, v30, v201
	v_mul_f32_e32 v30, v30, v142
	v_mul_f32_e32 v31, v31, v201
	v_mul_f32_e32 v31, v31, v143
	v_mul_f32_e32 v32, v32, v201
	v_mul_f32_e32 v32, v32, v144
	v_mul_f32_e32 v33, v33, v201
	v_mul_f32_e32 v33, v33, v145
	v_cvt_pk_bf16_f32 v30, v30, v31
	v_cvt_pk_bf16_f32 v31, v32, v33
	global_store_dwordx2 v[206:207], v[30:31], off offset:480
	v_readlane_b32 s28, v255, 4
	v_readlane_b32 s29, v255, 5
	s_mov_b32 s0, 0x3727c5ac

; __global__ void __launch_bounds__(512, 2) fwd_megakernel(Params p) {
;   extern __shared__ __attribute__((aligned(16))) unsigned char smem[];
;   cg::grid_group grid = cg::this_grid();
	.amdhsa_kernel _Z14fwd_megakernel6Params
		.amdhsa_group_segment_fixed_size 0
		.amdhsa_private_segment_fixed_size 0
		.amdhsa_kernarg_size 424
		.amdhsa_user_sgpr_count 2
		.amdhsa_user_sgpr_dispatch_ptr 0
		.amdhsa_user_sgpr_queue_ptr 0
		.amdhsa_user_sgpr_kernarg_segment_ptr 1
		.amdhsa_user_sgpr_dispatch_id 0
		.amdhsa_user_sgpr_kernarg_preload_length 0
		.amdhsa_user_sgpr_kernarg_preload_offset 0
		.amdhsa_user_sgpr_private_segment_size 0
		.amdhsa_uses_dynamic_stack 0
		.amdhsa_enable_private_segment 0
		.amdhsa_system_sgpr_workgroup_id_x 1
		.amdhsa_system_sgpr_workgroup_id_y 0
		.amdhsa_system_sgpr_workgroup_id_z 0
		.amdhsa_system_sgpr_workgroup_info 0
		.amdhsa_system_vgpr_workitem_id 2
		.amdhsa_next_free_vgpr 256
		.amdhsa_next_free_sgpr 102
		.amdhsa_accum_offset 256
		.amdhsa_reserve_vcc 1
		.amdhsa_float_round_mode_32 0
		.amdhsa_float_round_mode_16_64 0
		.amdhsa_float_denorm_mode_32 3
		.amdhsa_float_denorm_mode_16_64 3
		.amdhsa_dx10_clamp 1
		.amdhsa_ieee_mode 1
		.amdhsa_fp16_overflow 0
		.amdhsa_tg_split 0
		.amdhsa_exception_fp_ieee_invalid_op 0
		.amdhsa_exception_fp_denorm_src 0
		.amdhsa_exception_fp_ieee_div_zero 0
		.amdhsa_exception_fp_ieee_overflow 0
		.amdhsa_exception_fp_ieee_underflow 0
		.amdhsa_exception_fp_ieee_inexact 0
		.amdhsa_exception_int_div_zero 0
	.end_amdhsa_kernel

; __global__ void __launch_bounds__(512, 2) fwd_megakernel(Params p) {
;   extern __shared__ __attribute__((aligned(16))) unsigned char smem[];
;   cg::grid_group grid = cg::this_grid();
amdhsa.kernels:
  - .agpr_count:     0
    .args:
      - .offset:         0
        .size:           168
        .value_kind:     by_value
      - .offset:         168
        .size:           4
        .value_kind:     hidden_block_count_x
      - .offset:         172
        .size:           4
        .value_kind:     hidden_block_count_y
      - .offset:         176
        .size:           4
        .value_kind:     hidden_block_count_z
      - .offset:         180
        .size:           2
        .value_kind:     hidden_group_size_x
      - .offset:         182
        .size:           2
        .value_kind:     hidden_group_size_y
      - .offset:         184
        .size:           2
        .value_kind:     hidden_group_size_z
      - .offset:         186
        .size:           2
        .value_kind:     hidden_remainder_x
      - .offset:         188
        .size:           2
        .value_kind:     hidden_remainder_y
      - .offset:         190
        .size:           2
        .value_kind:     hidden_remainder_z
      - .offset:         208
        .size:           8
        .value_kind:     hidden_global_offset_x
      - .offset:         216
        .size:           8
        .value_kind:     hidden_global_offset_y
      - .offset:         224
        .size:           8
        .value_kind:     hidden_global_offset_z
      - .offset:         232
        .size:           2
        .value_kind:     hidden_grid_dims
      - .offset:         256
        .size:           8
        .value_kind:     hidden_multigrid_sync_arg
      - .offset:         288
        .size:           4
        .value_kind:     hidden_dynamic_lds_size
    .group_segment_fixed_size: 0
    .kernarg_segment_align: 8
    .kernarg_segment_size: 424
    .language:       OpenCL C
    .language_version:
      - 2
      - 0
    .max_flat_workgroup_size: 512
    .name:           _Z14fwd_megakernel6Params
    .private_segment_fixed_size: 0
    .sgpr_count:     108
    .sgpr_spill_count: 205
    .symbol:         _Z14fwd_megakernel6Params.kd
    .uniform_work_group_size: 1
    .uses_dynamic_stack: false
    .vgpr_count:     256
    .vgpr_spill_count: 0
    .wavefront_size: 64
